# plus accumulator zeroing at unit start with 64-bit moves (63 instead of 126 instructions per unit)
# speedup vs baseline: 1.0074x; 1.0074x over previous
; template <class Epi, class Sched, bool ALIGN_EPI = false, bool SP2 = false>
; __device__ __forceinline__ void gemm_phase(PG8_LAS unsigned char* lds, const Gemm g, const Sched& S, const Epi& E) {
;     ...
;         const bool has_next = S.next(ui + 1, nxt);
;         const char* nA = has_next ? (const char*)g.A + (size_t)nxt.pm * tstep : cA; const char* nB = has_next ? (const char*)g.Bt + (size_t)nxt.pn * tstep : cB;
;         for (int t = 0; t < nt; t += 2) {
;             const bool last = (t == nt - 2);
;             const char* a1 = cA + (size_t)(t + 1) * kstep;
;             const char* a2 = last ? nA : cA + (size_t)(t + 2) * kstep; const char* b2 = last ? nB : cB + (size_t)(t + 2) * kstep;
;             const char* a3 = a2 + kstep; const char* b3 = b2 + kstep;
;     ...
;         for (int a = 0; a < 2; ++a)
; #pragma unroll
;             for (int b = 0; b < 2; ++b)
; #pragma unroll
;                 for (int m = 0; m < 4; ++m)
; #pragma unroll
;                     for (int n = 0; n < 2; ++n) acc[a][b][m][n] = (f32x4){0.f, 0.f, 0.f, 0.f};
.LBB0_142:
	s_ashr_i32 s29, s28, 31
	s_lshl_b64 s[30:31], s[28:29], 19
	s_add_u32 s30, s54, s30
	s_addc_u32 s31, s55, s31
	s_and_b64 s[34:35], s[4:5], exec
	s_cselect_b32 s7, s31, s39
	s_cselect_b32 s29, s30, s38
	s_ashr_i32 s27, s26, 31
	s_lshl_b64 s[34:35], s[26:27], 19
	s_add_u32 s34, s62, s34
	s_addc_u32 s35, s63, s35
	s_and_b64 s[42:43], s[4:5], exec
	s_cselect_b32 s27, s35, s41
	s_cselect_b32 s82, s34, s40
	s_add_u32 s38, s38, 0x40080
	s_addc_u32 s39, s39, 0
	s_add_u32 s83, s40, 0x100
	v_mov_b32_e32 v0, 0
	s_addc_u32 s84, s41, 0
	s_mov_b32 s85, -2
	v_mov_b32_e32 v1, v0
	v_mov_b64_e32 v[2:3], v[0:1]
	v_mov_b64_e32 v[4:5], v[0:1]
	v_mov_b64_e32 v[6:7], v[0:1]
	v_mov_b64_e32 v[8:9], v[0:1]
	v_mov_b64_e32 v[10:11], v[0:1]
	v_mov_b64_e32 v[12:13], v[0:1]
	v_mov_b64_e32 v[14:15], v[0:1]
	v_mov_b64_e32 v[16:17], v[0:1]
	v_mov_b64_e32 v[18:19], v[0:1]
	v_mov_b64_e32 v[20:21], v[0:1]
	v_mov_b64_e32 v[22:23], v[0:1]
	v_mov_b64_e32 v[24:25], v[0:1]
	v_mov_b64_e32 v[26:27], v[0:1]
	v_mov_b64_e32 v[28:29], v[0:1]
	v_mov_b64_e32 v[30:31], v[0:1]
	v_mov_b64_e32 v[32:33], v[0:1]
	v_mov_b64_e32 v[34:35], v[0:1]
	v_mov_b64_e32 v[36:37], v[0:1]
	v_mov_b64_e32 v[38:39], v[0:1]
	v_mov_b64_e32 v[40:41], v[0:1]
	v_mov_b64_e32 v[42:43], v[0:1]
	v_mov_b64_e32 v[44:45], v[0:1]
	v_mov_b64_e32 v[46:47], v[0:1]
	v_mov_b64_e32 v[48:49], v[0:1]
	v_mov_b64_e32 v[50:51], v[0:1]
	v_mov_b64_e32 v[52:53], v[0:1]
	v_mov_b64_e32 v[54:55], v[0:1]
	v_mov_b64_e32 v[56:57], v[0:1]
	v_mov_b64_e32 v[58:59], v[0:1]
	v_mov_b64_e32 v[60:61], v[0:1]
	v_mov_b64_e32 v[62:63], v[0:1]
	v_mov_b64_e32 v[64:65], v[0:1]
	v_mov_b64_e32 v[66:67], v[0:1]
	v_mov_b64_e32 v[68:69], v[0:1]
	v_mov_b64_e32 v[70:71], v[0:1]
	v_mov_b64_e32 v[72:73], v[0:1]
	v_mov_b64_e32 v[74:75], v[0:1]
	v_mov_b64_e32 v[76:77], v[0:1]
	v_mov_b64_e32 v[78:79], v[0:1]
	v_mov_b64_e32 v[80:81], v[0:1]
	v_mov_b64_e32 v[82:83], v[0:1]
	v_mov_b64_e32 v[84:85], v[0:1]
	v_mov_b64_e32 v[86:87], v[0:1]
	v_mov_b64_e32 v[88:89], v[0:1]
	v_mov_b64_e32 v[90:91], v[0:1]
	v_mov_b64_e32 v[92:93], v[0:1]
	v_mov_b64_e32 v[94:95], v[0:1]
	v_mov_b64_e32 v[96:97], v[0:1]
	v_mov_b64_e32 v[98:99], v[0:1]
	v_mov_b64_e32 v[100:101], v[0:1]
	v_mov_b64_e32 v[102:103], v[0:1]
	v_mov_b64_e32 v[104:105], v[0:1]
	v_mov_b64_e32 v[106:107], v[0:1]
	v_mov_b64_e32 v[108:109], v[0:1]
	v_mov_b64_e32 v[110:111], v[0:1]
	v_mov_b64_e32 v[112:113], v[0:1]
	v_mov_b64_e32 v[114:115], v[0:1]
	v_mov_b64_e32 v[116:117], v[0:1]
	v_mov_b64_e32 v[118:119], v[0:1]
	v_mov_b64_e32 v[120:121], v[0:1]
	v_mov_b64_e32 v[122:123], v[0:1]
	v_mov_b64_e32 v[124:125], v[0:1]
	v_mov_b64_e32 v[126:127], v[0:1]

; template <class Epi, class Sched, bool ALIGN_EPI = false, bool SP2 = false>
; __device__ __forceinline__ void gemm_phase(PG8_LAS unsigned char* lds, const Gemm g, const Sched& S, const Epi& E) {
;     ...
;         const bool has_next = S.next(ui + 1, nxt);
;         const char* nA = has_next ? (const char*)g.A + (size_t)nxt.pm * tstep : cA; const char* nB = has_next ? (const char*)g.Bt + (size_t)nxt.pn * tstep : cB;
;         for (int t = 0; t < nt; t += 2) {
;             const bool last = (t == nt - 2);
;             const char* a1 = cA + (size_t)(t + 1) * kstep;
;             const char* a2 = last ? nA : cA + (size_t)(t + 2) * kstep; const char* b2 = last ? nB : cB + (size_t)(t + 2) * kstep;
;             const char* a3 = a2 + kstep; const char* b3 = b2 + kstep;
;     ...
;         for (int a = 0; a < 2; ++a)
; #pragma unroll
;             for (int b = 0; b < 2; ++b)
; #pragma unroll
;                 for (int m = 0; m < 4; ++m)
; #pragma unroll
;                     for (int n = 0; n < 2; ++n) acc[a][b][m][n] = (f32x4){0.f, 0.f, 0.f, 0.f};
.LBB0_182:
	s_ashr_i32 s37, s36, 31
	s_lshl_b64 s[38:39], s[36:37], 19
	s_add_u32 s38, s72, s38
	s_addc_u32 s39, s73, s39
	s_and_b64 s[40:41], s[28:29], exec
	s_cselect_b32 s37, s39, s43
	s_cselect_b32 s94, s38, s42
	s_ashr_i32 s35, s34, 31
	s_lshl_b64 s[40:41], s[34:35], 19
	s_add_u32 s40, s79, s40
	s_addc_u32 s41, s80, s41
	s_and_b64 s[64:65], s[28:29], exec
	s_cselect_b32 s35, s41, s63
	s_cselect_b32 s95, s40, s62
	s_add_u32 s42, s42, 0x40080
	s_addc_u32 s43, s43, 0
	s_add_u32 s96, s62, 0x100
	v_mov_b32_e32 v0, 0
	s_addc_u32 s97, s63, 0
	s_mov_b32 vcc_lo, -2
	v_mov_b32_e32 v1, v0
	v_mov_b64_e32 v[2:3], v[0:1]
	v_mov_b64_e32 v[4:5], v[0:1]
	v_mov_b64_e32 v[6:7], v[0:1]
	v_mov_b64_e32 v[8:9], v[0:1]
	v_mov_b64_e32 v[10:11], v[0:1]
	v_mov_b64_e32 v[12:13], v[0:1]
	v_mov_b64_e32 v[14:15], v[0:1]
	v_mov_b64_e32 v[16:17], v[0:1]
	v_mov_b64_e32 v[18:19], v[0:1]
	v_mov_b64_e32 v[20:21], v[0:1]
	v_mov_b64_e32 v[22:23], v[0:1]
	v_mov_b64_e32 v[24:25], v[0:1]
	v_mov_b64_e32 v[26:27], v[0:1]
	v_mov_b64_e32 v[28:29], v[0:1]
	v_mov_b64_e32 v[30:31], v[0:1]
	v_mov_b64_e32 v[32:33], v[0:1]
	v_mov_b64_e32 v[34:35], v[0:1]
	v_mov_b64_e32 v[36:37], v[0:1]
	v_mov_b64_e32 v[38:39], v[0:1]
	v_mov_b64_e32 v[40:41], v[0:1]
	v_mov_b64_e32 v[42:43], v[0:1]
	v_mov_b64_e32 v[44:45], v[0:1]
	v_mov_b64_e32 v[46:47], v[0:1]
	v_mov_b64_e32 v[48:49], v[0:1]
	v_mov_b64_e32 v[50:51], v[0:1]
	v_mov_b64_e32 v[52:53], v[0:1]
	v_mov_b64_e32 v[54:55], v[0:1]
	v_mov_b64_e32 v[56:57], v[0:1]
	v_mov_b64_e32 v[58:59], v[0:1]
	v_mov_b64_e32 v[60:61], v[0:1]
	v_mov_b64_e32 v[62:63], v[0:1]
	v_mov_b64_e32 v[64:65], v[0:1]
	v_mov_b64_e32 v[66:67], v[0:1]
	v_mov_b64_e32 v[68:69], v[0:1]
	v_mov_b64_e32 v[70:71], v[0:1]
	v_mov_b64_e32 v[72:73], v[0:1]
	v_mov_b64_e32 v[74:75], v[0:1]
	v_mov_b64_e32 v[76:77], v[0:1]
	v_mov_b64_e32 v[78:79], v[0:1]
	v_mov_b64_e32 v[80:81], v[0:1]
	v_mov_b64_e32 v[82:83], v[0:1]
	v_mov_b64_e32 v[84:85], v[0:1]
	v_mov_b64_e32 v[86:87], v[0:1]
	v_mov_b64_e32 v[88:89], v[0:1]
	v_mov_b64_e32 v[90:91], v[0:1]
	v_mov_b64_e32 v[92:93], v[0:1]
	v_mov_b64_e32 v[94:95], v[0:1]
	v_mov_b64_e32 v[96:97], v[0:1]
	v_mov_b64_e32 v[98:99], v[0:1]
	v_mov_b64_e32 v[100:101], v[0:1]
	v_mov_b64_e32 v[102:103], v[0:1]
	v_mov_b64_e32 v[104:105], v[0:1]
	v_mov_b64_e32 v[106:107], v[0:1]
	v_mov_b64_e32 v[108:109], v[0:1]
	v_mov_b64_e32 v[110:111], v[0:1]
	v_mov_b64_e32 v[112:113], v[0:1]
	v_mov_b64_e32 v[114:115], v[0:1]
	v_mov_b64_e32 v[116:117], v[0:1]
	v_mov_b64_e32 v[118:119], v[0:1]
	v_mov_b64_e32 v[120:121], v[0:1]
	v_mov_b64_e32 v[122:123], v[0:1]
	v_mov_b64_e32 v[124:125], v[0:1]
	v_mov_b64_e32 v[126:127], v[0:1]

; template <class Epi, class Sched, bool ALIGN_EPI = false, bool SP2 = false>
; __device__ __forceinline__ void gemm_phase(PG8_LAS unsigned char* lds, const Gemm g, const Sched& S, const Epi& E) {
;     ...
;         const bool has_next = S.next(ui + 1, nxt);
;         const char* nA = has_next ? (const char*)g.A + (size_t)nxt.pm * tstep : cA; const char* nB = has_next ? (const char*)g.Bt + (size_t)nxt.pn * tstep : cB;
;         for (int t = 0; t < nt; t += 2) {
;             const bool last = (t == nt - 2);
;             const char* a1 = cA + (size_t)(t + 1) * kstep;
;             const char* a2 = last ? nA : cA + (size_t)(t + 2) * kstep; const char* b2 = last ? nB : cB + (size_t)(t + 2) * kstep;
;             const char* a3 = a2 + kstep; const char* b3 = b2 + kstep;
;     ...
;         for (int a = 0; a < 2; ++a)
; #pragma unroll
;             for (int b = 0; b < 2; ++b)
; #pragma unroll
;                 for (int m = 0; m < 4; ++m)
; #pragma unroll
;                     for (int n = 0; n < 2; ++n) acc[a][b][m][n] = (f32x4){0.f, 0.f, 0.f, 0.f};
.LBB0_206:
	s_ashr_i32 s39, s38, 31
	s_lshl_b64 s[40:41], s[38:39], 19
	s_add_u32 s40, s77, s40
	s_addc_u32 s41, s79, s41
	s_and_b64 s[42:43], s[30:31], exec
	s_cselect_b32 s39, s41, s63
	s_cselect_b32 s93, s40, s62
	s_ashr_i32 s37, s36, 31
	s_lshl_b64 s[42:43], s[36:37], 19
	s_add_u32 s42, s72, s42
	s_addc_u32 s43, s73, s43
	s_and_b64 s[52:53], s[30:31], exec
	s_cselect_b32 s37, s43, s65
	s_cselect_b32 s94, s42, s64
	s_add_u32 s62, s62, 0x40080
	s_addc_u32 s63, s63, 0
	s_add_u32 s95, s64, 0x100
	v_mov_b32_e32 v0, 0
	s_addc_u32 s96, s65, 0
	s_mov_b32 s97, -2
	v_mov_b32_e32 v1, v0
	v_mov_b64_e32 v[2:3], v[0:1]
	v_mov_b64_e32 v[4:5], v[0:1]
	v_mov_b64_e32 v[6:7], v[0:1]
	v_mov_b64_e32 v[8:9], v[0:1]
	v_mov_b64_e32 v[10:11], v[0:1]
	v_mov_b64_e32 v[12:13], v[0:1]
	v_mov_b64_e32 v[14:15], v[0:1]
	v_mov_b64_e32 v[16:17], v[0:1]
	v_mov_b64_e32 v[18:19], v[0:1]
	v_mov_b64_e32 v[20:21], v[0:1]
	v_mov_b64_e32 v[22:23], v[0:1]
	v_mov_b64_e32 v[24:25], v[0:1]
	v_mov_b64_e32 v[26:27], v[0:1]
	v_mov_b64_e32 v[28:29], v[0:1]
	v_mov_b64_e32 v[30:31], v[0:1]
	v_mov_b64_e32 v[32:33], v[0:1]
	v_mov_b64_e32 v[34:35], v[0:1]
	v_mov_b64_e32 v[36:37], v[0:1]
	v_mov_b64_e32 v[38:39], v[0:1]
	v_mov_b64_e32 v[40:41], v[0:1]
	v_mov_b64_e32 v[42:43], v[0:1]
	v_mov_b64_e32 v[44:45], v[0:1]
	v_mov_b64_e32 v[46:47], v[0:1]
	v_mov_b64_e32 v[48:49], v[0:1]
	v_mov_b64_e32 v[50:51], v[0:1]
	v_mov_b64_e32 v[52:53], v[0:1]
	v_mov_b64_e32 v[54:55], v[0:1]
	v_mov_b64_e32 v[56:57], v[0:1]
	v_mov_b64_e32 v[58:59], v[0:1]
	v_mov_b64_e32 v[60:61], v[0:1]
	v_mov_b64_e32 v[62:63], v[0:1]
	v_mov_b64_e32 v[64:65], v[0:1]
	v_mov_b64_e32 v[66:67], v[0:1]
	v_mov_b64_e32 v[68:69], v[0:1]
	v_mov_b64_e32 v[70:71], v[0:1]
	v_mov_b64_e32 v[72:73], v[0:1]
	v_mov_b64_e32 v[74:75], v[0:1]
	v_mov_b64_e32 v[76:77], v[0:1]
	v_mov_b64_e32 v[78:79], v[0:1]
	v_mov_b64_e32 v[80:81], v[0:1]
	v_mov_b64_e32 v[82:83], v[0:1]
	v_mov_b64_e32 v[84:85], v[0:1]
	v_mov_b64_e32 v[86:87], v[0:1]
	v_mov_b64_e32 v[88:89], v[0:1]
	v_mov_b64_e32 v[90:91], v[0:1]
	v_mov_b64_e32 v[92:93], v[0:1]
	v_mov_b64_e32 v[94:95], v[0:1]
	v_mov_b64_e32 v[96:97], v[0:1]
	v_mov_b64_e32 v[98:99], v[0:1]
	v_mov_b64_e32 v[100:101], v[0:1]
	v_mov_b64_e32 v[102:103], v[0:1]
	v_mov_b64_e32 v[104:105], v[0:1]
	v_mov_b64_e32 v[106:107], v[0:1]
	v_mov_b64_e32 v[108:109], v[0:1]
	v_mov_b64_e32 v[110:111], v[0:1]
	v_mov_b64_e32 v[112:113], v[0:1]
	v_mov_b64_e32 v[114:115], v[0:1]
	v_mov_b64_e32 v[116:117], v[0:1]
	v_mov_b64_e32 v[118:119], v[0:1]
	v_mov_b64_e32 v[120:121], v[0:1]
	v_mov_b64_e32 v[122:123], v[0:1]
	v_mov_b64_e32 v[124:125], v[0:1]
	v_mov_b64_e32 v[126:127], v[0:1]

; #define PG8_STAGE(bufoff, gbase, voff) do { _Pragma("unroll") for (int _i = 0; _i < 2; ++_i) \
;         __builtin_amdgcn_global_load_lds((const unsigned*)((const char*)(gbase) + (voff)[_i]), (PG8_LAS unsigned*)(lds + (bufoff) + ldsw + _i * 8192), 16, 0, 0); } while (0)
; #define PG8_LDA(dst, b, h) do { _Pragma("unroll") for (int m = 0; m < 4; ++m) _Pragma("unroll") for (int k = 0; k < 2; ++k) dst[m][k] = *(const PG8_LAS bf16x8*)(lds + PG8_SA(b, h) + aoff + m * 2048 + k * 1024); } while (0)
; #define PG8_LDB(dst, b, h) do { _Pragma("unroll") for (int n = 0; n < 2; ++n) _Pragma("unroll") for (int k = 0; k < 2; ++k) dst[n][k] = *(const PG8_LAS bf16x8*)(lds + PG8_SB(b, h) + boff + n * 2048 + k * 1024); } while (0)
; #define PG8_MMA(ai, bj, At, Bt) do { __builtin_amdgcn_s_setprio(1); _Pragma("unroll") for (int m = 0; m < 4; ++m) _Pragma("unroll") for (int n = 0; n < 2; ++n) _Pragma("unroll") for (int k = 0; k < 2; ++k) \
;         acc[ai][bj][m][n] = __builtin_amdgcn_mfma_f32_16x16x32_bf16(Bt[n][k], At[m][k], acc[ai][bj][m][n], 0, 0, 0); __builtin_amdgcn_s_setprio(0); } while (0)
; #define PG8_WAIT_V(n) asm volatile("s_waitcnt vmcnt(" #n ")" ::: "memory")
; #define PG8_WAIT_L(n) asm volatile("s_waitcnt lgkmcnt(" #n ")" ::: "memory")
; #define PG8_BAR __builtin_amdgcn_s_barrier()
; #define PG8_SCHED __builtin_amdgcn_sched_barrier(0)
; template <class Epi, class Sched, bool ALIGN_EPI = false, bool SP2 = false>
; __device__ __forceinline__ void gemm_phase(PG8_LAS unsigned char* lds, const Gemm g, const Sched& S, const Epi& E) {
;     ...
;             PG8_LDB(B0, 0, 0); PG8_LDB(B1, 0, 1); PG8_SCHED; PG8_LDA(At, 0, 0); PG8_STAGE(PG8_SA(1, 1), a1 + hstep, voffA);
;             PG8_WAIT_V(8); PG8_WAIT_L(0); PG8_BAR; PG8_MMA(0, 0, At, B0); PG8_MMA(0, 1, At, B1); PG8_BAR; PG8_SCHED;
;             PG8_LDA(At, 0, 1); PG8_STAGE(PG8_SB(0, 0), b2, voffB); PG8_STAGE(PG8_SB(0, 1), b2 + hstep, voffB); PG8_STAGE(PG8_SA(0, 0), a2, voffA);
;             PG8_WAIT_V(8); PG8_WAIT_L(0); PG8_BAR; PG8_MMA(1, 0, At, B0); PG8_MMA(1, 1, At, B1); PG8_BAR; PG8_SCHED;
.LBB0_366:
	v_add_u32_e32 v153, s43, v151
	ds_read_b128 v[154:157], v153
	ds_read_b128 v[158:161], v153 offset:1024
	ds_read_b128 v[162:165], v153 offset:2048
	ds_read_b128 v[166:169], v153 offset:3072
	v_add_u32_e32 v153, s59, v151
	s_add_u32 s20, s12, s18
	ds_read_b128 v[170:173], v153
	ds_read_b128 v[174:177], v153 offset:1024
	ds_read_b128 v[178:181], v153 offset:2048
	ds_read_b128 v[182:185], v153 offset:3072
	s_addc_u32 s21, s13, s19
	s_add_u32 s20, s20, 0x100
	s_addc_u32 s21, s21, 0
	s_add_u32 s52, s64, s18
	s_addc_u32 s53, s65, s19
	s_cmpk_eq_i32 s18, 0x1500
	s_cselect_b32 s23, s17, s21
	s_cselect_b32 s22, s16, s20
	s_cselect_b32 s21, s9, s53
	s_cselect_b32 s20, s8, s52
	v_lshl_add_u64 v[206:207], v[144:145], 0, s[18:19]
	s_add_i32 m0, s34, 0xc000
	ds_read_b128 v[186:189], v152
	ds_read_b128 v[190:193], v152 offset:1024
	ds_read_b128 v[194:197], v152 offset:2048
	ds_read_b128 v[198:201], v152 offset:3072
	ds_read_b128 v[202:205], v152 offset:4096
	ds_read_b128 v[210:213], v152 offset:5120
	ds_read_b128 v[214:217], v152 offset:6144
	ds_read_b128 v[218:221], v152 offset:7168
	global_load_lds_dwordx4 v[206:207], off
	v_lshl_add_u64 v[206:207], v[146:147], 0, s[18:19]
	s_add_i32 m0, s34, 0xe000
	s_nop 0
	global_load_lds_dwordx4 v[206:207], off
	s_waitcnt vmcnt(8)
	s_waitcnt lgkmcnt(0)
	s_barrier
	s_setprio 1
	s_waitcnt lgkmcnt(0)
	v_mfma_f32_16x16x32_bf16 v[124:127], v[154:157], v[186:189], v[124:127]
	v_mfma_f32_16x16x32_bf16 v[120:123], v[162:165], v[186:189], v[120:123]
	v_mfma_f32_16x16x32_bf16 v[108:111], v[154:157], v[194:197], v[108:111]
	v_mfma_f32_16x16x32_bf16 v[104:107], v[162:165], v[194:197], v[104:107]
	v_mfma_f32_16x16x32_bf16 v[92:95], v[154:157], v[202:205], v[92:95]
	v_mfma_f32_16x16x32_bf16 v[88:91], v[162:165], v[202:205], v[88:91]
	v_mfma_f32_16x16x32_bf16 v[76:79], v[154:157], v[214:217], v[76:79]
	v_mfma_f32_16x16x32_bf16 v[72:75], v[162:165], v[214:217], v[72:75]
	v_mfma_f32_16x16x32_bf16 v[124:127], v[158:161], v[190:193], v[124:127]
	v_mfma_f32_16x16x32_bf16 v[120:123], v[166:169], v[190:193], v[120:123]
	v_mfma_f32_16x16x32_bf16 v[108:111], v[158:161], v[198:201], v[108:111]
	v_mfma_f32_16x16x32_bf16 v[104:107], v[166:169], v[198:201], v[104:107]
	v_mfma_f32_16x16x32_bf16 v[92:95], v[158:161], v[210:213], v[92:95]
	v_mfma_f32_16x16x32_bf16 v[88:91], v[166:169], v[210:213], v[88:91]
	v_mfma_f32_16x16x32_bf16 v[76:79], v[158:161], v[218:221], v[76:79]
	v_mfma_f32_16x16x32_bf16 v[72:75], v[166:169], v[218:221], v[72:75]
	s_setprio 0
	s_setprio 1
	v_mfma_f32_16x16x32_bf16 v[116:119], v[170:173], v[186:189], v[116:119]
	v_mfma_f32_16x16x32_bf16 v[112:115], v[178:181], v[186:189], v[112:115]
	v_mfma_f32_16x16x32_bf16 v[100:103], v[170:173], v[194:197], v[100:103]
	v_mfma_f32_16x16x32_bf16 v[96:99], v[178:181], v[194:197], v[96:99]
	v_mfma_f32_16x16x32_bf16 v[84:87], v[170:173], v[202:205], v[84:87]
	v_mfma_f32_16x16x32_bf16 v[80:83], v[178:181], v[202:205], v[80:83]
	v_mfma_f32_16x16x32_bf16 v[68:71], v[170:173], v[214:217], v[68:71]
	v_mfma_f32_16x16x32_bf16 v[64:67], v[178:181], v[214:217], v[64:67]
	v_mfma_f32_16x16x32_bf16 v[116:119], v[174:177], v[190:193], v[116:119]
	v_mfma_f32_16x16x32_bf16 v[112:115], v[182:185], v[190:193], v[112:115]
	v_mfma_f32_16x16x32_bf16 v[100:103], v[174:177], v[198:201], v[100:103]
	v_mfma_f32_16x16x32_bf16 v[96:99], v[182:185], v[198:201], v[96:99]
	v_mfma_f32_16x16x32_bf16 v[84:87], v[174:177], v[210:213], v[84:87]
	v_mfma_f32_16x16x32_bf16 v[80:83], v[182:185], v[210:213], v[80:83]
	v_mfma_f32_16x16x32_bf16 v[68:71], v[174:177], v[218:221], v[68:71]
	s_barrier
	v_mfma_f32_16x16x32_bf16 v[64:67], v[182:185], v[218:221], v[64:67]
	s_setprio 0
	s_add_i32 s52, s43, s29
	v_lshl_add_u64 v[206:207], s[20:21], 0, v[130:131]
	s_mov_b32 m0, s52
	ds_read_b128 v[186:189], v152 offset:16384
	ds_read_b128 v[190:193], v152 offset:17408
	ds_read_b128 v[194:197], v152 offset:18432
	ds_read_b128 v[198:201], v152 offset:19456
	ds_read_b128 v[202:205], v152 offset:20480
	ds_read_b128 v[210:213], v152 offset:21504
	ds_read_b128 v[214:217], v152 offset:22528
	ds_read_b128 v[218:221], v152 offset:23552
	global_load_lds_dwordx4 v[206:207], off
	s_add_i32 m0, s52, 0x2000
	s_add_u32 s52, s20, 0xb0000
	v_lshl_add_u64 v[222:223], s[20:21], 0, v[134:135]
	s_addc_u32 s53, s21, 0
	s_add_i32 s67, s59, s29
	global_load_lds_dwordx4 v[222:223], off
	v_lshl_add_u64 v[224:225], s[52:53], 0, v[130:131]
	s_mov_b32 m0, s67
	v_lshl_add_u64 v[226:227], s[22:23], 0, v[132:133]
	global_load_lds_dwordx4 v[224:225], off
	v_lshl_add_u64 v[224:225], s[52:53], 0, v[134:135]
	s_add_i32 m0, s67, 0x2000
	s_nop 0
	global_load_lds_dwordx4 v[224:225], off
	v_lshl_add_u64 v[224:225], s[22:23], 0, v[128:129]
	s_mov_b32 m0, s34
	s_nop 0
	global_load_lds_dwordx4 v[224:225], off
	s_mov_b32 m0, s35
	s_nop 0
	global_load_lds_dwordx4 v[226:227], off
	s_waitcnt vmcnt(8)
	s_waitcnt lgkmcnt(0)
	s_barrier
; #define PG8_STAGE(bufoff, gbase, voff) do { _Pragma("unroll") for (int _i = 0; _i < 2; ++_i) \
;         __builtin_amdgcn_global_load_lds((const unsigned*)((const char*)(gbase) + (voff)[_i]), (PG8_LAS unsigned*)(lds + (bufoff) + ldsw + _i * 8192), 16, 0, 0); } while (0)
; #define PG8_LDA(dst, b, h) do { _Pragma("unroll") for (int m = 0; m < 4; ++m) _Pragma("unroll") for (int k = 0; k < 2; ++k) dst[m][k] = *(const PG8_LAS bf16x8*)(lds + PG8_SA(b, h) + aoff + m * 2048 + k * 1024); } while (0)
; #define PG8_LDB(dst, b, h) do { _Pragma("unroll") for (int n = 0; n < 2; ++n) _Pragma("unroll") for (int k = 0; k < 2; ++k) dst[n][k] = *(const PG8_LAS bf16x8*)(lds + PG8_SB(b, h) + boff + n * 2048 + k * 1024); } while (0)
; #define PG8_MMA(ai, bj, At, Bt) do { __builtin_amdgcn_s_setprio(1); _Pragma("unroll") for (int m = 0; m < 4; ++m) _Pragma("unroll") for (int n = 0; n < 2; ++n) _Pragma("unroll") for (int k = 0; k < 2; ++k) \
;         acc[ai][bj][m][n] = __builtin_amdgcn_mfma_f32_16x16x32_bf16(Bt[n][k], At[m][k], acc[ai][bj][m][n], 0, 0, 0); __builtin_amdgcn_s_setprio(0); } while (0)
; #define PG8_WAIT_V(n) asm volatile("s_waitcnt vmcnt(" #n ")" ::: "memory")
; #define PG8_WAIT_L(n) asm volatile("s_waitcnt lgkmcnt(" #n ")" ::: "memory")
; #define PG8_BAR __builtin_amdgcn_s_barrier()
; #define PG8_SCHED __builtin_amdgcn_sched_barrier(0)
; template <class Epi, class Sched, bool ALIGN_EPI = false, bool SP2 = false>
; __device__ __forceinline__ void gemm_phase(PG8_LAS unsigned char* lds, const Gemm g, const Sched& S, const Epi& E) {
;     ...
;             PG8_WAIT_V(8); PG8_WAIT_L(0); PG8_BAR; PG8_MMA(1, 0, At, B0); PG8_MMA(1, 1, At, B1); PG8_BAR; PG8_SCHED;
;             PG8_LDB(B0, 1, 0); PG8_LDB(B1, 1, 1); PG8_SCHED; PG8_LDA(At, 1, 0); PG8_STAGE(PG8_SA(0, 1), a2 + hstep, voffA);
;             PG8_WAIT_V(8); PG8_WAIT_L(0); PG8_BAR; PG8_MMA(0, 0, At, B0); PG8_MMA(0, 1, At, B1); PG8_BAR; PG8_SCHED;
	s_setprio 1
	s_waitcnt lgkmcnt(0)
	v_mfma_f32_16x16x32_bf16 v[60:63], v[154:157], v[186:189], v[60:63]
	v_mfma_f32_16x16x32_bf16 v[56:59], v[162:165], v[186:189], v[56:59]
	v_mfma_f32_16x16x32_bf16 v[44:47], v[154:157], v[194:197], v[44:47]
	v_mfma_f32_16x16x32_bf16 v[40:43], v[162:165], v[194:197], v[40:43]
	v_mfma_f32_16x16x32_bf16 v[28:31], v[154:157], v[202:205], v[28:31]
	v_mfma_f32_16x16x32_bf16 v[24:27], v[162:165], v[202:205], v[24:27]
	v_mfma_f32_16x16x32_bf16 v[12:15], v[154:157], v[214:217], v[12:15]
	v_mfma_f32_16x16x32_bf16 v[8:11], v[162:165], v[214:217], v[8:11]
	v_mfma_f32_16x16x32_bf16 v[60:63], v[158:161], v[190:193], v[60:63]
	v_mfma_f32_16x16x32_bf16 v[56:59], v[166:169], v[190:193], v[56:59]
	v_mfma_f32_16x16x32_bf16 v[44:47], v[158:161], v[198:201], v[44:47]
	v_mfma_f32_16x16x32_bf16 v[40:43], v[166:169], v[198:201], v[40:43]
	v_mfma_f32_16x16x32_bf16 v[28:31], v[158:161], v[210:213], v[28:31]
	v_mfma_f32_16x16x32_bf16 v[24:27], v[166:169], v[210:213], v[24:27]
	v_mfma_f32_16x16x32_bf16 v[12:15], v[158:161], v[218:221], v[12:15]
	v_mfma_f32_16x16x32_bf16 v[8:11], v[166:169], v[218:221], v[8:11]
	s_setprio 0
	s_setprio 1
	v_mfma_f32_16x16x32_bf16 v[52:55], v[170:173], v[186:189], v[52:55]
	v_mfma_f32_16x16x32_bf16 v[48:51], v[178:181], v[186:189], v[48:51]
	v_mfma_f32_16x16x32_bf16 v[36:39], v[170:173], v[194:197], v[36:39]
	v_mfma_f32_16x16x32_bf16 v[32:35], v[178:181], v[194:197], v[32:35]
	v_mfma_f32_16x16x32_bf16 v[20:23], v[170:173], v[202:205], v[20:23]
	v_mfma_f32_16x16x32_bf16 v[16:19], v[178:181], v[202:205], v[16:19]
	v_mfma_f32_16x16x32_bf16 v[4:7], v[170:173], v[214:217], v[4:7]
	v_mfma_f32_16x16x32_bf16 v[0:3], v[178:181], v[214:217], v[0:3]
	v_mfma_f32_16x16x32_bf16 v[52:55], v[174:177], v[190:193], v[52:55]
	v_mfma_f32_16x16x32_bf16 v[48:51], v[182:185], v[190:193], v[48:51]
	v_mfma_f32_16x16x32_bf16 v[36:39], v[174:177], v[198:201], v[36:39]
	v_mfma_f32_16x16x32_bf16 v[32:35], v[182:185], v[198:201], v[32:35]
	v_mfma_f32_16x16x32_bf16 v[20:23], v[174:177], v[210:213], v[20:23]
	v_mfma_f32_16x16x32_bf16 v[16:19], v[182:185], v[210:213], v[16:19]
	v_mfma_f32_16x16x32_bf16 v[4:7], v[174:177], v[218:221], v[4:7]
	s_barrier
	v_mfma_f32_16x16x32_bf16 v[0:3], v[182:185], v[218:221], v[0:3]
	s_setprio 0
	s_add_i32 s52, 0, 0x18000
	v_add_u32_e32 v153, s52, v151
	s_add_i32 s53, 0, 0x1c000
	ds_read_b128 v[154:157], v153
	ds_read_b128 v[158:161], v153 offset:1024
	ds_read_b128 v[162:165], v153 offset:2048
	ds_read_b128 v[166:169], v153 offset:3072
	v_add_u32_e32 v153, s53, v151
	ds_read_b128 v[170:173], v153
	ds_read_b128 v[174:177], v153 offset:1024
	ds_read_b128 v[178:181], v153 offset:2048
	ds_read_b128 v[182:185], v153 offset:3072
	s_add_u32 s22, s22, 0xb0000
	s_addc_u32 s23, s23, 0
	s_mov_b32 m0, s36
	v_lshl_add_u64 v[228:229], s[22:23], 0, v[128:129]
	ds_read_b128 v[186:189], v152 offset:32768
	ds_read_b128 v[190:193], v152 offset:33792
	ds_read_b128 v[194:197], v152 offset:34816
	ds_read_b128 v[198:201], v152 offset:35840
	ds_read_b128 v[202:205], v152 offset:36864
	ds_read_b128 v[210:213], v152 offset:37888
	ds_read_b128 v[214:217], v152 offset:38912
	ds_read_b128 v[218:221], v152 offset:39936
	global_load_lds_dwordx4 v[228:229], off
	v_lshl_add_u64 v[228:229], s[22:23], 0, v[132:133]
	s_mov_b32 m0, s37
	s_nop 0
	global_load_lds_dwordx4 v[228:229], off
	s_waitcnt vmcnt(8)
	s_waitcnt lgkmcnt(0)
	s_barrier
	s_setprio 1
	s_waitcnt lgkmcnt(0)
	v_mfma_f32_16x16x32_bf16 v[124:127], v[154:157], v[186:189], v[124:127]
	v_mfma_f32_16x16x32_bf16 v[120:123], v[162:165], v[186:189], v[120:123]
	v_mfma_f32_16x16x32_bf16 v[108:111], v[154:157], v[194:197], v[108:111]
	v_mfma_f32_16x16x32_bf16 v[104:107], v[162:165], v[194:197], v[104:107]
	v_mfma_f32_16x16x32_bf16 v[92:95], v[154:157], v[202:205], v[92:95]
	v_mfma_f32_16x16x32_bf16 v[88:91], v[162:165], v[202:205], v[88:91]
	v_mfma_f32_16x16x32_bf16 v[76:79], v[154:157], v[214:217], v[76:79]
	v_mfma_f32_16x16x32_bf16 v[72:75], v[162:165], v[214:217], v[72:75]
	v_mfma_f32_16x16x32_bf16 v[124:127], v[158:161], v[190:193], v[124:127]
	v_mfma_f32_16x16x32_bf16 v[120:123], v[166:169], v[190:193], v[120:123]
	v_mfma_f32_16x16x32_bf16 v[108:111], v[158:161], v[198:201], v[108:111]
	v_mfma_f32_16x16x32_bf16 v[104:107], v[166:169], v[198:201], v[104:107]
	v_mfma_f32_16x16x32_bf16 v[92:95], v[158:161], v[210:213], v[92:95]
	v_mfma_f32_16x16x32_bf16 v[88:91], v[166:169], v[210:213], v[88:91]
	v_mfma_f32_16x16x32_bf16 v[76:79], v[158:161], v[218:221], v[76:79]
	v_mfma_f32_16x16x32_bf16 v[72:75], v[166:169], v[218:221], v[72:75]
	s_setprio 0
	s_setprio 1
	v_mfma_f32_16x16x32_bf16 v[116:119], v[170:173], v[186:189], v[116:119]
	v_mfma_f32_16x16x32_bf16 v[112:115], v[178:181], v[186:189], v[112:115]
	v_mfma_f32_16x16x32_bf16 v[100:103], v[170:173], v[194:197], v[100:103]
	v_mfma_f32_16x16x32_bf16 v[96:99], v[178:181], v[194:197], v[96:99]
	v_mfma_f32_16x16x32_bf16 v[84:87], v[170:173], v[202:205], v[84:87]
	v_mfma_f32_16x16x32_bf16 v[80:83], v[178:181], v[202:205], v[80:83]
	v_mfma_f32_16x16x32_bf16 v[68:71], v[170:173], v[214:217], v[68:71]
	v_mfma_f32_16x16x32_bf16 v[64:67], v[178:181], v[214:217], v[64:67]
	v_mfma_f32_16x16x32_bf16 v[116:119], v[174:177], v[190:193], v[116:119]
	v_mfma_f32_16x16x32_bf16 v[112:115], v[182:185], v[190:193], v[112:115]
	v_mfma_f32_16x16x32_bf16 v[100:103], v[174:177], v[198:201], v[100:103]
	v_mfma_f32_16x16x32_bf16 v[96:99], v[182:185], v[198:201], v[96:99]
	v_mfma_f32_16x16x32_bf16 v[84:87], v[174:177], v[210:213], v[84:87]
	v_mfma_f32_16x16x32_bf16 v[80:83], v[182:185], v[210:213], v[80:83]
	v_mfma_f32_16x16x32_bf16 v[68:71], v[174:177], v[218:221], v[68:71]
	s_barrier
; #define PG8_STAGE(bufoff, gbase, voff) do { _Pragma("unroll") for (int _i = 0; _i < 2; ++_i) \
;         __builtin_amdgcn_global_load_lds((const unsigned*)((const char*)(gbase) + (voff)[_i]), (PG8_LAS unsigned*)(lds + (bufoff) + ldsw + _i * 8192), 16, 0, 0); } while (0)
; #define PG8_LDA(dst, b, h) do { _Pragma("unroll") for (int m = 0; m < 4; ++m) _Pragma("unroll") for (int k = 0; k < 2; ++k) dst[m][k] = *(const PG8_LAS bf16x8*)(lds + PG8_SA(b, h) + aoff + m * 2048 + k * 1024); } while (0)
; #define PG8_MMA(ai, bj, At, Bt) do { __builtin_amdgcn_s_setprio(1); _Pragma("unroll") for (int m = 0; m < 4; ++m) _Pragma("unroll") for (int n = 0; n < 2; ++n) _Pragma("unroll") for (int k = 0; k < 2; ++k) \
;         acc[ai][bj][m][n] = __builtin_amdgcn_mfma_f32_16x16x32_bf16(Bt[n][k], At[m][k], acc[ai][bj][m][n], 0, 0, 0); __builtin_amdgcn_s_setprio(0); } while (0)
; #define PG8_WAIT_V(n) asm volatile("s_waitcnt vmcnt(" #n ")" ::: "memory")
; #define PG8_WAIT_L(n) asm volatile("s_waitcnt lgkmcnt(" #n ")" ::: "memory")
; #define PG8_BAR __builtin_amdgcn_s_barrier()
; #define PG8_SCHED __builtin_amdgcn_sched_barrier(0)
; template <class Epi, class Sched, bool ALIGN_EPI = false, bool SP2 = false>
; __device__ __forceinline__ void gemm_phase(PG8_LAS unsigned char* lds, const Gemm g, const Sched& S, const Epi& E) {
;     ...
;             PG8_LDA(At, 1, 1); PG8_STAGE(PG8_SB(1, 0), b3, voffB); PG8_STAGE(PG8_SB(1, 1), b3 + hstep, voffB); PG8_STAGE(PG8_SA(1, 0), a3, voffA);
;             PG8_WAIT_V(8); PG8_WAIT_L(0); PG8_BAR; PG8_MMA(1, 0, At, B0); PG8_MMA(1, 1, At, B1); PG8_BAR; PG8_SCHED;
;     ...
;         if (!has_next) break;
; #pragma unroll
;         for (int a = 0; a < 2; ++a)
; #pragma unroll
;             for (int b = 0; b < 2; ++b)
; #pragma unroll
;                 for (int m = 0; m < 4; ++m)
; #pragma unroll
;                     for (int n = 0; n < 2; ++n) acc[a][b][m][n] = (f32x4){0.f, 0.f, 0.f, 0.f};
;         cur = nxt; cA = nA; cB = nB; ++ui;
	v_mfma_f32_16x16x32_bf16 v[64:67], v[182:185], v[218:221], v[64:67]
	s_setprio 0
	s_add_i32 s22, s52, s29
	v_lshl_add_u64 v[206:207], v[206:207], 0, s[14:15]
	s_mov_b32 m0, s22
	ds_read_b128 v[186:189], v152 offset:49152
	ds_read_b128 v[190:193], v152 offset:50176
	ds_read_b128 v[194:197], v152 offset:51200
	ds_read_b128 v[198:201], v152 offset:52224
	ds_read_b128 v[202:205], v152 offset:53248
	ds_read_b128 v[210:213], v152 offset:54272
	ds_read_b128 v[214:217], v152 offset:55296
	ds_read_b128 v[218:221], v152 offset:56320
	global_load_lds_dwordx4 v[206:207], off
	s_add_i32 m0, s22, 0x2000
	s_add_u32 s20, s20, 0xb0080
	v_lshl_add_u64 v[206:207], v[222:223], 0, s[14:15]
	s_addc_u32 s21, s21, 0
	s_add_i32 s22, s53, s29
	global_load_lds_dwordx4 v[206:207], off
	v_lshl_add_u64 v[206:207], s[20:21], 0, v[130:131]
	s_mov_b32 m0, s22
	s_nop 0
	global_load_lds_dwordx4 v[206:207], off
	v_lshl_add_u64 v[206:207], s[20:21], 0, v[134:135]
	s_add_i32 m0, s22, 0x2000
	s_nop 0
	global_load_lds_dwordx4 v[206:207], off
	v_lshl_add_u64 v[206:207], v[224:225], 0, s[14:15]
	s_mov_b32 m0, s39
	s_nop 0
	global_load_lds_dwordx4 v[206:207], off
	v_lshl_add_u64 v[206:207], v[226:227], 0, s[14:15]
	s_mov_b32 m0, s40
	s_nop 0
	global_load_lds_dwordx4 v[206:207], off
	s_waitcnt vmcnt(8)
	s_waitcnt lgkmcnt(0)
	s_barrier
	s_setprio 1
	s_waitcnt lgkmcnt(0)
	v_mfma_f32_16x16x32_bf16 v[60:63], v[154:157], v[186:189], v[60:63]
	v_mfma_f32_16x16x32_bf16 v[56:59], v[162:165], v[186:189], v[56:59]
	v_mfma_f32_16x16x32_bf16 v[44:47], v[154:157], v[194:197], v[44:47]
	v_mfma_f32_16x16x32_bf16 v[40:43], v[162:165], v[194:197], v[40:43]
	v_mfma_f32_16x16x32_bf16 v[28:31], v[154:157], v[202:205], v[28:31]
	v_mfma_f32_16x16x32_bf16 v[24:27], v[162:165], v[202:205], v[24:27]
	v_mfma_f32_16x16x32_bf16 v[12:15], v[154:157], v[214:217], v[12:15]
	v_mfma_f32_16x16x32_bf16 v[8:11], v[162:165], v[214:217], v[8:11]
	v_mfma_f32_16x16x32_bf16 v[60:63], v[158:161], v[190:193], v[60:63]
	v_mfma_f32_16x16x32_bf16 v[56:59], v[166:169], v[190:193], v[56:59]
	v_mfma_f32_16x16x32_bf16 v[44:47], v[158:161], v[198:201], v[44:47]
	v_mfma_f32_16x16x32_bf16 v[40:43], v[166:169], v[198:201], v[40:43]
	v_mfma_f32_16x16x32_bf16 v[28:31], v[158:161], v[210:213], v[28:31]
	v_mfma_f32_16x16x32_bf16 v[24:27], v[166:169], v[210:213], v[24:27]
	v_mfma_f32_16x16x32_bf16 v[12:15], v[158:161], v[218:221], v[12:15]
	v_mfma_f32_16x16x32_bf16 v[8:11], v[166:169], v[218:221], v[8:11]
	s_setprio 0
	s_setprio 1
	v_mfma_f32_16x16x32_bf16 v[52:55], v[170:173], v[186:189], v[52:55]
	v_mfma_f32_16x16x32_bf16 v[48:51], v[178:181], v[186:189], v[48:51]
	v_mfma_f32_16x16x32_bf16 v[36:39], v[170:173], v[194:197], v[36:39]
	v_mfma_f32_16x16x32_bf16 v[32:35], v[178:181], v[194:197], v[32:35]
	v_mfma_f32_16x16x32_bf16 v[20:23], v[170:173], v[202:205], v[20:23]
	v_mfma_f32_16x16x32_bf16 v[16:19], v[178:181], v[202:205], v[16:19]
	v_mfma_f32_16x16x32_bf16 v[4:7], v[170:173], v[214:217], v[4:7]
	v_mfma_f32_16x16x32_bf16 v[0:3], v[178:181], v[214:217], v[0:3]
	v_mfma_f32_16x16x32_bf16 v[52:55], v[174:177], v[190:193], v[52:55]
	v_mfma_f32_16x16x32_bf16 v[48:51], v[182:185], v[190:193], v[48:51]
	v_mfma_f32_16x16x32_bf16 v[36:39], v[174:177], v[198:201], v[36:39]
	v_mfma_f32_16x16x32_bf16 v[32:35], v[182:185], v[198:201], v[32:35]
	v_mfma_f32_16x16x32_bf16 v[20:23], v[174:177], v[210:213], v[20:23]
	v_mfma_f32_16x16x32_bf16 v[16:19], v[182:185], v[210:213], v[16:19]
	v_mfma_f32_16x16x32_bf16 v[4:7], v[174:177], v[218:221], v[4:7]
	s_barrier
	v_mfma_f32_16x16x32_bf16 v[0:3], v[182:185], v[218:221], v[0:3]
	s_setprio 0
	s_add_i32 s66, s66, 2
	s_add_u32 s18, s18, 0x100
	s_addc_u32 s19, s19, 0
	s_cmp_gt_u32 s66, 41
	s_cbranch_scc0 .LBB0_366
	s_add_u32 s18, s64, 0xffffff00
	s_addc_u32 s19, s65, -1
	s_and_b64 vcc, exec, s[6:7]
	s_cbranch_vccnz .LBB0_369
	v_mov_b32_e32 v0, 0
	s_mov_b32 s41, s61
	s_mov_b32 s31, s62
	s_mov_b64 s[12:13], s[16:17]
	s_mov_b32 s42, s63
	v_mov_b32_e32 v1, v0
	v_mov_b64_e32 v[2:3], v[0:1]
	v_mov_b64_e32 v[4:5], v[0:1]
	v_mov_b64_e32 v[6:7], v[0:1]
	v_mov_b64_e32 v[8:9], v[0:1]
	v_mov_b64_e32 v[10:11], v[0:1]
	v_mov_b64_e32 v[12:13], v[0:1]
	v_mov_b64_e32 v[14:15], v[0:1]
	v_mov_b64_e32 v[16:17], v[0:1]
	v_mov_b64_e32 v[18:19], v[0:1]
	v_mov_b64_e32 v[20:21], v[0:1]
	v_mov_b64_e32 v[22:23], v[0:1]
	v_mov_b64_e32 v[24:25], v[0:1]
	v_mov_b64_e32 v[26:27], v[0:1]
	v_mov_b64_e32 v[28:29], v[0:1]
	v_mov_b64_e32 v[30:31], v[0:1]
	v_mov_b64_e32 v[32:33], v[0:1]
	v_mov_b64_e32 v[34:35], v[0:1]
	v_mov_b64_e32 v[36:37], v[0:1]
	v_mov_b64_e32 v[38:39], v[0:1]
	v_mov_b64_e32 v[40:41], v[0:1]
	v_mov_b64_e32 v[42:43], v[0:1]
	v_mov_b64_e32 v[44:45], v[0:1]
	v_mov_b64_e32 v[46:47], v[0:1]
	v_mov_b64_e32 v[48:49], v[0:1]
	v_mov_b64_e32 v[50:51], v[0:1]
	v_mov_b64_e32 v[52:53], v[0:1]
	v_mov_b64_e32 v[54:55], v[0:1]
	v_mov_b64_e32 v[56:57], v[0:1]
	v_mov_b64_e32 v[58:59], v[0:1]
	v_mov_b64_e32 v[60:61], v[0:1]
	v_mov_b64_e32 v[62:63], v[0:1]
	v_mov_b64_e32 v[64:65], v[0:1]
	v_mov_b64_e32 v[66:67], v[0:1]
	v_mov_b64_e32 v[68:69], v[0:1]
	v_mov_b64_e32 v[70:71], v[0:1]
	v_mov_b64_e32 v[72:73], v[0:1]
	v_mov_b64_e32 v[74:75], v[0:1]
	v_mov_b64_e32 v[76:77], v[0:1]
	v_mov_b64_e32 v[78:79], v[0:1]
	v_mov_b64_e32 v[80:81], v[0:1]
	v_mov_b64_e32 v[82:83], v[0:1]
	v_mov_b64_e32 v[84:85], v[0:1]
	v_mov_b64_e32 v[86:87], v[0:1]
	v_mov_b64_e32 v[88:89], v[0:1]
	v_mov_b64_e32 v[90:91], v[0:1]
	v_mov_b64_e32 v[92:93], v[0:1]
	v_mov_b64_e32 v[94:95], v[0:1]
	v_mov_b64_e32 v[96:97], v[0:1]
	v_mov_b64_e32 v[98:99], v[0:1]
	v_mov_b64_e32 v[100:101], v[0:1]
	v_mov_b64_e32 v[102:103], v[0:1]
	v_mov_b64_e32 v[104:105], v[0:1]
	v_mov_b64_e32 v[106:107], v[0:1]
	v_mov_b64_e32 v[108:109], v[0:1]
	v_mov_b64_e32 v[110:111], v[0:1]
	v_mov_b64_e32 v[112:113], v[0:1]
	v_mov_b64_e32 v[114:115], v[0:1]
	v_mov_b64_e32 v[116:117], v[0:1]
	v_mov_b64_e32 v[118:119], v[0:1]
	v_mov_b64_e32 v[120:121], v[0:1]
	v_mov_b64_e32 v[122:123], v[0:1]
	v_mov_b64_e32 v[124:125], v[0:1]
	v_mov_b64_e32 v[126:127], v[0:1]
	s_andn2_b64 vcc, exec, s[4:5]
	s_cbranch_vccnz .LBB0_370
	s_branch .LBB0_371

; template <class Epi, class Sched, bool ALIGN_EPI = false, bool SP2 = false>
; __device__ __forceinline__ void gemm_phase(PG8_LAS unsigned char* lds, const Gemm g, const Sched& S, const Epi& E) {
;     ...
;         const bool has_next = S.next(ui + 1, nxt);
;         const char* nA = has_next ? (const char*)g.A + (size_t)nxt.pm * tstep : cA; const char* nB = has_next ? (const char*)g.Bt + (size_t)nxt.pn * tstep : cB;
;         for (int t = 0; t < nt; t += 2) {
;             const bool last = (t == nt - 2);
;             const char* a1 = cA + (size_t)(t + 1) * kstep;
;             const char* a2 = last ? nA : cA + (size_t)(t + 2) * kstep; const char* b2 = last ? nB : cB + (size_t)(t + 2) * kstep;
;             const char* a3 = a2 + kstep; const char* b3 = b2 + kstep;
;     ...
;         for (int a = 0; a < 2; ++a)
; #pragma unroll
;             for (int b = 0; b < 2; ++b)
; #pragma unroll
;                 for (int m = 0; m < 4; ++m)
; #pragma unroll
;                     for (int n = 0; n < 2; ++n) acc[a][b][m][n] = (f32x4){0.f, 0.f, 0.f, 0.f};
.LBB0_461:
	s_ashr_i32 s67, s66, 31
	s_lshl_b64 s[52:53], s[66:67], 19
	s_add_u32 s68, s54, s52
	s_addc_u32 s69, s55, s53
	s_and_b64 s[52:53], s[4:5], exec
	s_cselect_b32 s7, s69, s9
	s_cselect_b32 s67, s68, s8
	s_ashr_i32 s65, s64, 31
	s_lshl_b64 s[52:53], s[64:65], 19
	s_add_u32 s70, s25, s52
	s_addc_u32 s71, s59, s53
	s_and_b64 s[52:53], s[4:5], exec
	s_cselect_b32 s65, s71, s73
	s_cselect_b32 s95, s70, s72
	s_add_u32 s8, s8, 0x40080
	s_addc_u32 s9, s9, 0
	s_add_u32 s96, s72, 0x100
	v_mov_b32_e32 v0, 0
	s_addc_u32 s97, s73, 0
	s_mov_b32 vcc_lo, -2
	v_mov_b32_e32 v1, v0
	v_mov_b64_e32 v[2:3], v[0:1]
	v_mov_b64_e32 v[4:5], v[0:1]
	v_mov_b64_e32 v[6:7], v[0:1]
	v_mov_b64_e32 v[8:9], v[0:1]
	v_mov_b64_e32 v[10:11], v[0:1]
	v_mov_b64_e32 v[12:13], v[0:1]
	v_mov_b64_e32 v[14:15], v[0:1]
	v_mov_b64_e32 v[16:17], v[0:1]
	v_mov_b64_e32 v[18:19], v[0:1]
	v_mov_b64_e32 v[20:21], v[0:1]
	v_mov_b64_e32 v[22:23], v[0:1]
	v_mov_b64_e32 v[24:25], v[0:1]
	v_mov_b64_e32 v[26:27], v[0:1]
	v_mov_b64_e32 v[28:29], v[0:1]
	v_mov_b64_e32 v[30:31], v[0:1]
	v_mov_b64_e32 v[32:33], v[0:1]
	v_mov_b64_e32 v[34:35], v[0:1]
	v_mov_b64_e32 v[36:37], v[0:1]
	v_mov_b64_e32 v[38:39], v[0:1]
	v_mov_b64_e32 v[40:41], v[0:1]
	v_mov_b64_e32 v[42:43], v[0:1]
	v_mov_b64_e32 v[44:45], v[0:1]
	v_mov_b64_e32 v[46:47], v[0:1]
	v_mov_b64_e32 v[48:49], v[0:1]
	v_mov_b64_e32 v[50:51], v[0:1]
	v_mov_b64_e32 v[52:53], v[0:1]
	v_mov_b64_e32 v[54:55], v[0:1]
	v_mov_b64_e32 v[56:57], v[0:1]
	v_mov_b64_e32 v[58:59], v[0:1]
	v_mov_b64_e32 v[60:61], v[0:1]
	v_mov_b64_e32 v[62:63], v[0:1]
	v_mov_b64_e32 v[64:65], v[0:1]
	v_mov_b64_e32 v[66:67], v[0:1]
	v_mov_b64_e32 v[68:69], v[0:1]
	v_mov_b64_e32 v[70:71], v[0:1]
	v_mov_b64_e32 v[72:73], v[0:1]
	v_mov_b64_e32 v[74:75], v[0:1]
	v_mov_b64_e32 v[76:77], v[0:1]
	v_mov_b64_e32 v[78:79], v[0:1]
	v_mov_b64_e32 v[80:81], v[0:1]
	v_mov_b64_e32 v[82:83], v[0:1]
	v_mov_b64_e32 v[84:85], v[0:1]
	v_mov_b64_e32 v[86:87], v[0:1]
	v_mov_b64_e32 v[88:89], v[0:1]
	v_mov_b64_e32 v[90:91], v[0:1]
	v_mov_b64_e32 v[92:93], v[0:1]
	v_mov_b64_e32 v[94:95], v[0:1]
	v_mov_b64_e32 v[96:97], v[0:1]
	v_mov_b64_e32 v[98:99], v[0:1]
	v_mov_b64_e32 v[100:101], v[0:1]
	v_mov_b64_e32 v[102:103], v[0:1]
	v_mov_b64_e32 v[104:105], v[0:1]
	v_mov_b64_e32 v[106:107], v[0:1]
	v_mov_b64_e32 v[108:109], v[0:1]
	v_mov_b64_e32 v[110:111], v[0:1]
	v_mov_b64_e32 v[112:113], v[0:1]
	v_mov_b64_e32 v[114:115], v[0:1]
	v_mov_b64_e32 v[116:117], v[0:1]
	v_mov_b64_e32 v[118:119], v[0:1]
	v_mov_b64_e32 v[120:121], v[0:1]
	v_mov_b64_e32 v[122:123], v[0:1]
	v_mov_b64_e32 v[124:125], v[0:1]
	v_mov_b64_e32 v[126:127], v[0:1]

; template <class Epi, class Sched, bool ALIGN_EPI = false, bool SP2 = false>
; __device__ __forceinline__ void gemm_phase(PG8_LAS unsigned char* lds, const Gemm g, const Sched& S, const Epi& E) {
;     ...
;         const bool has_next = S.next(ui + 1, nxt);
;         const char* nA = has_next ? (const char*)g.A + (size_t)nxt.pm * tstep : cA; const char* nB = has_next ? (const char*)g.Bt + (size_t)nxt.pn * tstep : cB;
;         for (int t = 0; t < nt; t += 2) {
;             const bool last = (t == nt - 2);
;             const char* a1 = cA + (size_t)(t + 1) * kstep;
;             const char* a2 = last ? nA : cA + (size_t)(t + 2) * kstep; const char* b2 = last ? nB : cB + (size_t)(t + 2) * kstep;
;             const char* a3 = a2 + kstep; const char* b3 = b2 + kstep;
;     ...
;         for (int a = 0; a < 2; ++a)
; #pragma unroll
;             for (int b = 0; b < 2; ++b)
; #pragma unroll
;                 for (int m = 0; m < 4; ++m)
; #pragma unroll
;                     for (int n = 0; n < 2; ++n) acc[a][b][m][n] = (f32x4){0.f, 0.f, 0.f, 0.f};
.LBB0_595:
	s_ashr_i32 s67, s66, 31
	s_lshl_b64 s[52:53], s[66:67], 19
	s_add_u32 s68, s54, s52
	s_addc_u32 s69, s55, s53
	s_and_b64 s[52:53], s[4:5], exec
	s_cselect_b32 s7, s69, s73
	s_cselect_b32 s9, s68, s72
	s_ashr_i32 s65, s64, 31
	s_lshl_b64 s[52:53], s[64:65], 19
	s_add_u32 s70, s79, s52
	s_addc_u32 s71, s80, s53
	s_and_b64 s[52:53], s[4:5], exec
	s_cselect_b32 s18, s71, s75
	s_cselect_b32 s65, s70, s74
	s_add_u32 s72, s72, 0x40080
	s_addc_u32 s73, s73, 0
	s_add_u32 s67, s74, 0x100
	v_mov_b32_e32 v0, 0
	s_addc_u32 vcc_lo, s75, 0
	s_mov_b32 vcc_hi, -2
	v_mov_b32_e32 v1, v0
	v_mov_b64_e32 v[2:3], v[0:1]
	v_mov_b64_e32 v[4:5], v[0:1]
	v_mov_b64_e32 v[6:7], v[0:1]
	v_mov_b64_e32 v[8:9], v[0:1]
	v_mov_b64_e32 v[10:11], v[0:1]
	v_mov_b64_e32 v[12:13], v[0:1]
	v_mov_b64_e32 v[14:15], v[0:1]
	v_mov_b64_e32 v[16:17], v[0:1]
	v_mov_b64_e32 v[18:19], v[0:1]
	v_mov_b64_e32 v[20:21], v[0:1]
	v_mov_b64_e32 v[22:23], v[0:1]
	v_mov_b64_e32 v[24:25], v[0:1]
	v_mov_b64_e32 v[26:27], v[0:1]
	v_mov_b64_e32 v[28:29], v[0:1]
	v_mov_b64_e32 v[30:31], v[0:1]
	v_mov_b64_e32 v[32:33], v[0:1]
	v_mov_b64_e32 v[34:35], v[0:1]
	v_mov_b64_e32 v[36:37], v[0:1]
	v_mov_b64_e32 v[38:39], v[0:1]
	v_mov_b64_e32 v[40:41], v[0:1]
	v_mov_b64_e32 v[42:43], v[0:1]
	v_mov_b64_e32 v[44:45], v[0:1]
	v_mov_b64_e32 v[46:47], v[0:1]
	v_mov_b64_e32 v[48:49], v[0:1]
	v_mov_b64_e32 v[50:51], v[0:1]
	v_mov_b64_e32 v[52:53], v[0:1]
	v_mov_b64_e32 v[54:55], v[0:1]
	v_mov_b64_e32 v[56:57], v[0:1]
	v_mov_b64_e32 v[58:59], v[0:1]
	v_mov_b64_e32 v[60:61], v[0:1]
	v_mov_b64_e32 v[62:63], v[0:1]
	v_mov_b64_e32 v[64:65], v[0:1]
	v_mov_b64_e32 v[66:67], v[0:1]
	v_mov_b64_e32 v[68:69], v[0:1]
	v_mov_b64_e32 v[70:71], v[0:1]
	v_mov_b64_e32 v[72:73], v[0:1]
	v_mov_b64_e32 v[74:75], v[0:1]
	v_mov_b64_e32 v[76:77], v[0:1]
	v_mov_b64_e32 v[78:79], v[0:1]
	v_mov_b64_e32 v[80:81], v[0:1]
	v_mov_b64_e32 v[82:83], v[0:1]
	v_mov_b64_e32 v[84:85], v[0:1]
	v_mov_b64_e32 v[86:87], v[0:1]
	v_mov_b64_e32 v[88:89], v[0:1]
	v_mov_b64_e32 v[90:91], v[0:1]
	v_mov_b64_e32 v[92:93], v[0:1]
	v_mov_b64_e32 v[94:95], v[0:1]
	v_mov_b64_e32 v[96:97], v[0:1]
	v_mov_b64_e32 v[98:99], v[0:1]
	v_mov_b64_e32 v[100:101], v[0:1]
	v_mov_b64_e32 v[102:103], v[0:1]
	v_mov_b64_e32 v[104:105], v[0:1]
	v_mov_b64_e32 v[106:107], v[0:1]
	v_mov_b64_e32 v[108:109], v[0:1]
	v_mov_b64_e32 v[110:111], v[0:1]
	v_mov_b64_e32 v[112:113], v[0:1]
	v_mov_b64_e32 v[114:115], v[0:1]
	v_mov_b64_e32 v[116:117], v[0:1]
	v_mov_b64_e32 v[118:119], v[0:1]
	v_mov_b64_e32 v[120:121], v[0:1]
	v_mov_b64_e32 v[122:123], v[0:1]
	v_mov_b64_e32 v[124:125], v[0:1]
	v_mov_b64_e32 v[126:127], v[0:1]

; #define PG8_STAGE(bufoff, gbase, voff) do { _Pragma("unroll") for (int _i = 0; _i < 2; ++_i) \
;         __builtin_amdgcn_global_load_lds((const unsigned*)((const char*)(gbase) + (voff)[_i]), (PG8_LAS unsigned*)(lds + (bufoff) + ldsw + _i * 8192), 16, 0, 0); } while (0)
; #define PG8_LDA(dst, b, h) do { _Pragma("unroll") for (int m = 0; m < 4; ++m) _Pragma("unroll") for (int k = 0; k < 2; ++k) dst[m][k] = *(const PG8_LAS bf16x8*)(lds + PG8_SA(b, h) + aoff + m * 2048 + k * 1024); } while (0)
; #define PG8_LDB(dst, b, h) do { _Pragma("unroll") for (int n = 0; n < 2; ++n) _Pragma("unroll") for (int k = 0; k < 2; ++k) dst[n][k] = *(const PG8_LAS bf16x8*)(lds + PG8_SB(b, h) + boff + n * 2048 + k * 1024); } while (0)
; #define PG8_MMA(ai, bj, At, Bt) do { __builtin_amdgcn_s_setprio(1); _Pragma("unroll") for (int m = 0; m < 4; ++m) _Pragma("unroll") for (int n = 0; n < 2; ++n) _Pragma("unroll") for (int k = 0; k < 2; ++k) \
;         acc[ai][bj][m][n] = __builtin_amdgcn_mfma_f32_16x16x32_bf16(Bt[n][k], At[m][k], acc[ai][bj][m][n], 0, 0, 0); __builtin_amdgcn_s_setprio(0); } while (0)
; #define PG8_WAIT_V(n) asm volatile("s_waitcnt vmcnt(" #n ")" ::: "memory")
; #define PG8_WAIT_L(n) asm volatile("s_waitcnt lgkmcnt(" #n ")" ::: "memory")
; #define PG8_BAR __builtin_amdgcn_s_barrier()
; #define PG8_SCHED __builtin_amdgcn_sched_barrier(0)
; template <class Epi, class Sched, bool ALIGN_EPI = false, bool SP2 = false>
; __device__ __forceinline__ void gemm_phase(PG8_LAS unsigned char* lds, const Gemm g, const Sched& S, const Epi& E) {
;     ...
;             PG8_LDB(B0, 0, 0); PG8_LDB(B1, 0, 1); PG8_SCHED; PG8_LDA(At, 0, 0); PG8_STAGE(PG8_SA(1, 1), a1 + hstep, voffA);
;             PG8_WAIT_V(8); PG8_WAIT_L(0); PG8_BAR; PG8_MMA(0, 0, At, B0); PG8_MMA(0, 1, At, B1); PG8_BAR; PG8_SCHED;
;             PG8_LDA(At, 0, 1); PG8_STAGE(PG8_SB(0, 0), b2, voffB); PG8_STAGE(PG8_SB(0, 1), b2 + hstep, voffB); PG8_STAGE(PG8_SA(0, 0), a2, voffA);
;             PG8_WAIT_V(8); PG8_WAIT_L(0); PG8_BAR; PG8_MMA(1, 0, At, B0); PG8_MMA(1, 1, At, B1); PG8_BAR; PG8_SCHED;
.LBB0_1009:
	v_add_u32_e32 v153, s63, v151
	ds_read_b128 v[154:157], v153
	ds_read_b128 v[158:161], v153 offset:1024
	ds_read_b128 v[162:165], v153 offset:2048
	ds_read_b128 v[166:169], v153 offset:3072
	v_add_u32_e32 v153, s64, v151
	s_add_u32 s26, s12, s24
	ds_read_b128 v[170:173], v153
	ds_read_b128 v[174:177], v153 offset:1024
	ds_read_b128 v[178:181], v153 offset:2048
	ds_read_b128 v[182:185], v153 offset:3072
	s_addc_u32 s27, s13, s25
	s_add_u32 s26, s26, 0x100
	s_addc_u32 s27, s27, 0
	s_add_u32 s52, s66, s24
	s_addc_u32 s53, s67, s25
	s_cmpk_eq_i32 s24, 0x700
	s_cselect_b32 s29, s19, s27
	s_cselect_b32 s28, s68, s26
	s_cselect_b32 s27, s17, s53
	s_cselect_b32 s26, s69, s52
	v_lshl_add_u64 v[206:207], v[144:145], 0, s[24:25]
	s_add_i32 m0, s39, 0xc000
	ds_read_b128 v[186:189], v152
	ds_read_b128 v[190:193], v152 offset:1024
	ds_read_b128 v[194:197], v152 offset:2048
	ds_read_b128 v[198:201], v152 offset:3072
	ds_read_b128 v[202:205], v152 offset:4096
	ds_read_b128 v[210:213], v152 offset:5120
	ds_read_b128 v[214:217], v152 offset:6144
	ds_read_b128 v[218:221], v152 offset:7168
	global_load_lds_dwordx4 v[206:207], off
	v_lshl_add_u64 v[206:207], v[146:147], 0, s[24:25]
	s_add_i32 m0, s39, 0xe000
	s_nop 0
	global_load_lds_dwordx4 v[206:207], off
	s_waitcnt vmcnt(8)
	s_waitcnt lgkmcnt(0)
	s_barrier
	s_setprio 1
	s_waitcnt lgkmcnt(0)
	v_mfma_f32_16x16x32_bf16 v[124:127], v[154:157], v[186:189], v[124:127]
	v_mfma_f32_16x16x32_bf16 v[120:123], v[162:165], v[186:189], v[120:123]
	v_mfma_f32_16x16x32_bf16 v[108:111], v[154:157], v[194:197], v[108:111]
	v_mfma_f32_16x16x32_bf16 v[104:107], v[162:165], v[194:197], v[104:107]
	v_mfma_f32_16x16x32_bf16 v[92:95], v[154:157], v[202:205], v[92:95]
	v_mfma_f32_16x16x32_bf16 v[88:91], v[162:165], v[202:205], v[88:91]
	v_mfma_f32_16x16x32_bf16 v[76:79], v[154:157], v[214:217], v[76:79]
	v_mfma_f32_16x16x32_bf16 v[72:75], v[162:165], v[214:217], v[72:75]
	v_mfma_f32_16x16x32_bf16 v[124:127], v[158:161], v[190:193], v[124:127]
	v_mfma_f32_16x16x32_bf16 v[120:123], v[166:169], v[190:193], v[120:123]
	v_mfma_f32_16x16x32_bf16 v[108:111], v[158:161], v[198:201], v[108:111]
	v_mfma_f32_16x16x32_bf16 v[104:107], v[166:169], v[198:201], v[104:107]
	v_mfma_f32_16x16x32_bf16 v[92:95], v[158:161], v[210:213], v[92:95]
	v_mfma_f32_16x16x32_bf16 v[88:91], v[166:169], v[210:213], v[88:91]
	v_mfma_f32_16x16x32_bf16 v[76:79], v[158:161], v[218:221], v[76:79]
	v_mfma_f32_16x16x32_bf16 v[72:75], v[166:169], v[218:221], v[72:75]
	s_setprio 0
	s_setprio 1
	v_mfma_f32_16x16x32_bf16 v[116:119], v[170:173], v[186:189], v[116:119]
	v_mfma_f32_16x16x32_bf16 v[112:115], v[178:181], v[186:189], v[112:115]
	v_mfma_f32_16x16x32_bf16 v[100:103], v[170:173], v[194:197], v[100:103]
	v_mfma_f32_16x16x32_bf16 v[96:99], v[178:181], v[194:197], v[96:99]
	v_mfma_f32_16x16x32_bf16 v[84:87], v[170:173], v[202:205], v[84:87]
	v_mfma_f32_16x16x32_bf16 v[80:83], v[178:181], v[202:205], v[80:83]
	v_mfma_f32_16x16x32_bf16 v[68:71], v[170:173], v[214:217], v[68:71]
	v_mfma_f32_16x16x32_bf16 v[64:67], v[178:181], v[214:217], v[64:67]
	v_mfma_f32_16x16x32_bf16 v[116:119], v[174:177], v[190:193], v[116:119]
	v_mfma_f32_16x16x32_bf16 v[112:115], v[182:185], v[190:193], v[112:115]
	v_mfma_f32_16x16x32_bf16 v[100:103], v[174:177], v[198:201], v[100:103]
	v_mfma_f32_16x16x32_bf16 v[96:99], v[182:185], v[198:201], v[96:99]
	v_mfma_f32_16x16x32_bf16 v[84:87], v[174:177], v[210:213], v[84:87]
	v_mfma_f32_16x16x32_bf16 v[80:83], v[182:185], v[210:213], v[80:83]
	v_mfma_f32_16x16x32_bf16 v[68:71], v[174:177], v[218:221], v[68:71]
	s_barrier
	v_mfma_f32_16x16x32_bf16 v[64:67], v[182:185], v[218:221], v[64:67]
	s_setprio 0
	s_add_i32 s52, s63, s38
	v_lshl_add_u64 v[206:207], s[26:27], 0, v[130:131]
	s_mov_b32 m0, s52
	ds_read_b128 v[186:189], v152 offset:16384
	ds_read_b128 v[190:193], v152 offset:17408
	ds_read_b128 v[194:197], v152 offset:18432
	ds_read_b128 v[198:201], v152 offset:19456
	ds_read_b128 v[202:205], v152 offset:20480
	ds_read_b128 v[210:213], v152 offset:21504
	ds_read_b128 v[214:217], v152 offset:22528
	ds_read_b128 v[218:221], v152 offset:23552
	global_load_lds_dwordx4 v[206:207], off
	s_add_i32 m0, s52, 0x2000
	s_add_u32 s52, s26, 0x40000
	v_lshl_add_u64 v[222:223], s[26:27], 0, v[134:135]
	s_addc_u32 s53, s27, 0
	s_add_i32 s71, s64, s38
	global_load_lds_dwordx4 v[222:223], off
	v_lshl_add_u64 v[224:225], s[52:53], 0, v[130:131]
	s_mov_b32 m0, s71
	v_lshl_add_u64 v[226:227], s[28:29], 0, v[132:133]
	global_load_lds_dwordx4 v[224:225], off
	v_lshl_add_u64 v[224:225], s[52:53], 0, v[134:135]
	s_add_i32 m0, s71, 0x2000
	s_nop 0
	global_load_lds_dwordx4 v[224:225], off
	v_lshl_add_u64 v[224:225], s[28:29], 0, v[128:129]
	s_mov_b32 m0, s39
	s_nop 0
	global_load_lds_dwordx4 v[224:225], off
	s_mov_b32 m0, s40
	s_nop 0
	global_load_lds_dwordx4 v[226:227], off
	s_waitcnt vmcnt(8)
	s_waitcnt lgkmcnt(0)
	s_barrier
; #define PG8_STAGE(bufoff, gbase, voff) do { _Pragma("unroll") for (int _i = 0; _i < 2; ++_i) \
;         __builtin_amdgcn_global_load_lds((const unsigned*)((const char*)(gbase) + (voff)[_i]), (PG8_LAS unsigned*)(lds + (bufoff) + ldsw + _i * 8192), 16, 0, 0); } while (0)
; #define PG8_LDA(dst, b, h) do { _Pragma("unroll") for (int m = 0; m < 4; ++m) _Pragma("unroll") for (int k = 0; k < 2; ++k) dst[m][k] = *(const PG8_LAS bf16x8*)(lds + PG8_SA(b, h) + aoff + m * 2048 + k * 1024); } while (0)
; #define PG8_LDB(dst, b, h) do { _Pragma("unroll") for (int n = 0; n < 2; ++n) _Pragma("unroll") for (int k = 0; k < 2; ++k) dst[n][k] = *(const PG8_LAS bf16x8*)(lds + PG8_SB(b, h) + boff + n * 2048 + k * 1024); } while (0)
; #define PG8_MMA(ai, bj, At, Bt) do { __builtin_amdgcn_s_setprio(1); _Pragma("unroll") for (int m = 0; m < 4; ++m) _Pragma("unroll") for (int n = 0; n < 2; ++n) _Pragma("unroll") for (int k = 0; k < 2; ++k) \
;         acc[ai][bj][m][n] = __builtin_amdgcn_mfma_f32_16x16x32_bf16(Bt[n][k], At[m][k], acc[ai][bj][m][n], 0, 0, 0); __builtin_amdgcn_s_setprio(0); } while (0)
; #define PG8_WAIT_V(n) asm volatile("s_waitcnt vmcnt(" #n ")" ::: "memory")
; #define PG8_WAIT_L(n) asm volatile("s_waitcnt lgkmcnt(" #n ")" ::: "memory")
; #define PG8_BAR __builtin_amdgcn_s_barrier()
; #define PG8_SCHED __builtin_amdgcn_sched_barrier(0)
; template <class Epi, class Sched, bool ALIGN_EPI = false, bool SP2 = false>
; __device__ __forceinline__ void gemm_phase(PG8_LAS unsigned char* lds, const Gemm g, const Sched& S, const Epi& E) {
;     ...
;             PG8_WAIT_V(8); PG8_WAIT_L(0); PG8_BAR; PG8_MMA(1, 0, At, B0); PG8_MMA(1, 1, At, B1); PG8_BAR; PG8_SCHED;
;             PG8_LDB(B0, 1, 0); PG8_LDB(B1, 1, 1); PG8_SCHED; PG8_LDA(At, 1, 0); PG8_STAGE(PG8_SA(0, 1), a2 + hstep, voffA);
;             PG8_WAIT_V(8); PG8_WAIT_L(0); PG8_BAR; PG8_MMA(0, 0, At, B0); PG8_MMA(0, 1, At, B1); PG8_BAR; PG8_SCHED;
	s_setprio 1
	s_waitcnt lgkmcnt(0)
	v_mfma_f32_16x16x32_bf16 v[60:63], v[154:157], v[186:189], v[60:63]
	v_mfma_f32_16x16x32_bf16 v[56:59], v[162:165], v[186:189], v[56:59]
	v_mfma_f32_16x16x32_bf16 v[44:47], v[154:157], v[194:197], v[44:47]
	v_mfma_f32_16x16x32_bf16 v[40:43], v[162:165], v[194:197], v[40:43]
	v_mfma_f32_16x16x32_bf16 v[28:31], v[154:157], v[202:205], v[28:31]
	v_mfma_f32_16x16x32_bf16 v[24:27], v[162:165], v[202:205], v[24:27]
	v_mfma_f32_16x16x32_bf16 v[12:15], v[154:157], v[214:217], v[12:15]
	v_mfma_f32_16x16x32_bf16 v[8:11], v[162:165], v[214:217], v[8:11]
	v_mfma_f32_16x16x32_bf16 v[60:63], v[158:161], v[190:193], v[60:63]
	v_mfma_f32_16x16x32_bf16 v[56:59], v[166:169], v[190:193], v[56:59]
	v_mfma_f32_16x16x32_bf16 v[44:47], v[158:161], v[198:201], v[44:47]
	v_mfma_f32_16x16x32_bf16 v[40:43], v[166:169], v[198:201], v[40:43]
	v_mfma_f32_16x16x32_bf16 v[28:31], v[158:161], v[210:213], v[28:31]
	v_mfma_f32_16x16x32_bf16 v[24:27], v[166:169], v[210:213], v[24:27]
	v_mfma_f32_16x16x32_bf16 v[12:15], v[158:161], v[218:221], v[12:15]
	v_mfma_f32_16x16x32_bf16 v[8:11], v[166:169], v[218:221], v[8:11]
	s_setprio 0
	s_setprio 1
	v_mfma_f32_16x16x32_bf16 v[52:55], v[170:173], v[186:189], v[52:55]
	v_mfma_f32_16x16x32_bf16 v[48:51], v[178:181], v[186:189], v[48:51]
	v_mfma_f32_16x16x32_bf16 v[36:39], v[170:173], v[194:197], v[36:39]
	v_mfma_f32_16x16x32_bf16 v[32:35], v[178:181], v[194:197], v[32:35]
	v_mfma_f32_16x16x32_bf16 v[20:23], v[170:173], v[202:205], v[20:23]
	v_mfma_f32_16x16x32_bf16 v[16:19], v[178:181], v[202:205], v[16:19]
	v_mfma_f32_16x16x32_bf16 v[4:7], v[170:173], v[214:217], v[4:7]
	v_mfma_f32_16x16x32_bf16 v[0:3], v[178:181], v[214:217], v[0:3]
	v_mfma_f32_16x16x32_bf16 v[52:55], v[174:177], v[190:193], v[52:55]
	v_mfma_f32_16x16x32_bf16 v[48:51], v[182:185], v[190:193], v[48:51]
	v_mfma_f32_16x16x32_bf16 v[36:39], v[174:177], v[198:201], v[36:39]
	v_mfma_f32_16x16x32_bf16 v[32:35], v[182:185], v[198:201], v[32:35]
	v_mfma_f32_16x16x32_bf16 v[20:23], v[174:177], v[210:213], v[20:23]
	v_mfma_f32_16x16x32_bf16 v[16:19], v[182:185], v[210:213], v[16:19]
	v_mfma_f32_16x16x32_bf16 v[4:7], v[174:177], v[218:221], v[4:7]
	s_barrier
	v_mfma_f32_16x16x32_bf16 v[0:3], v[182:185], v[218:221], v[0:3]
	s_setprio 0
	s_add_i32 s52, 0, 0x18000
	v_add_u32_e32 v153, s52, v151
	s_add_i32 s53, 0, 0x1c000
	ds_read_b128 v[154:157], v153
	ds_read_b128 v[158:161], v153 offset:1024
	ds_read_b128 v[162:165], v153 offset:2048
	ds_read_b128 v[166:169], v153 offset:3072
	v_add_u32_e32 v153, s53, v151
	ds_read_b128 v[170:173], v153
	ds_read_b128 v[174:177], v153 offset:1024
	ds_read_b128 v[178:181], v153 offset:2048
	ds_read_b128 v[182:185], v153 offset:3072
	s_add_u32 s28, s28, 0x40000
	s_addc_u32 s29, s29, 0
	s_mov_b32 m0, s41
	v_lshl_add_u64 v[228:229], s[28:29], 0, v[128:129]
	ds_read_b128 v[186:189], v152 offset:32768
	ds_read_b128 v[190:193], v152 offset:33792
	ds_read_b128 v[194:197], v152 offset:34816
	ds_read_b128 v[198:201], v152 offset:35840
	ds_read_b128 v[202:205], v152 offset:36864
	ds_read_b128 v[210:213], v152 offset:37888
	ds_read_b128 v[214:217], v152 offset:38912
	ds_read_b128 v[218:221], v152 offset:39936
	global_load_lds_dwordx4 v[228:229], off
	v_lshl_add_u64 v[228:229], s[28:29], 0, v[132:133]
	s_mov_b32 m0, s42
	s_nop 0
	global_load_lds_dwordx4 v[228:229], off
	s_waitcnt vmcnt(8)
	s_waitcnt lgkmcnt(0)
	s_barrier
	s_setprio 1
	s_waitcnt lgkmcnt(0)
	v_mfma_f32_16x16x32_bf16 v[124:127], v[154:157], v[186:189], v[124:127]
	v_mfma_f32_16x16x32_bf16 v[120:123], v[162:165], v[186:189], v[120:123]
	v_mfma_f32_16x16x32_bf16 v[108:111], v[154:157], v[194:197], v[108:111]
	v_mfma_f32_16x16x32_bf16 v[104:107], v[162:165], v[194:197], v[104:107]
	v_mfma_f32_16x16x32_bf16 v[92:95], v[154:157], v[202:205], v[92:95]
	v_mfma_f32_16x16x32_bf16 v[88:91], v[162:165], v[202:205], v[88:91]
	v_mfma_f32_16x16x32_bf16 v[76:79], v[154:157], v[214:217], v[76:79]
	v_mfma_f32_16x16x32_bf16 v[72:75], v[162:165], v[214:217], v[72:75]
	v_mfma_f32_16x16x32_bf16 v[124:127], v[158:161], v[190:193], v[124:127]
	v_mfma_f32_16x16x32_bf16 v[120:123], v[166:169], v[190:193], v[120:123]
	v_mfma_f32_16x16x32_bf16 v[108:111], v[158:161], v[198:201], v[108:111]
	v_mfma_f32_16x16x32_bf16 v[104:107], v[166:169], v[198:201], v[104:107]
	v_mfma_f32_16x16x32_bf16 v[92:95], v[158:161], v[210:213], v[92:95]
	v_mfma_f32_16x16x32_bf16 v[88:91], v[166:169], v[210:213], v[88:91]
	v_mfma_f32_16x16x32_bf16 v[76:79], v[158:161], v[218:221], v[76:79]
	v_mfma_f32_16x16x32_bf16 v[72:75], v[166:169], v[218:221], v[72:75]
	s_setprio 0
	s_setprio 1
	v_mfma_f32_16x16x32_bf16 v[116:119], v[170:173], v[186:189], v[116:119]
	v_mfma_f32_16x16x32_bf16 v[112:115], v[178:181], v[186:189], v[112:115]
	v_mfma_f32_16x16x32_bf16 v[100:103], v[170:173], v[194:197], v[100:103]
	v_mfma_f32_16x16x32_bf16 v[96:99], v[178:181], v[194:197], v[96:99]
	v_mfma_f32_16x16x32_bf16 v[84:87], v[170:173], v[202:205], v[84:87]
	v_mfma_f32_16x16x32_bf16 v[80:83], v[178:181], v[202:205], v[80:83]
	v_mfma_f32_16x16x32_bf16 v[68:71], v[170:173], v[214:217], v[68:71]
	v_mfma_f32_16x16x32_bf16 v[64:67], v[178:181], v[214:217], v[64:67]
	v_mfma_f32_16x16x32_bf16 v[116:119], v[174:177], v[190:193], v[116:119]
	v_mfma_f32_16x16x32_bf16 v[112:115], v[182:185], v[190:193], v[112:115]
	v_mfma_f32_16x16x32_bf16 v[100:103], v[174:177], v[198:201], v[100:103]
	v_mfma_f32_16x16x32_bf16 v[96:99], v[182:185], v[198:201], v[96:99]
	v_mfma_f32_16x16x32_bf16 v[84:87], v[174:177], v[210:213], v[84:87]
	v_mfma_f32_16x16x32_bf16 v[80:83], v[182:185], v[210:213], v[80:83]
	v_mfma_f32_16x16x32_bf16 v[68:71], v[174:177], v[218:221], v[68:71]
	s_barrier
; #define PG8_STAGE(bufoff, gbase, voff) do { _Pragma("unroll") for (int _i = 0; _i < 2; ++_i) \
;         __builtin_amdgcn_global_load_lds((const unsigned*)((const char*)(gbase) + (voff)[_i]), (PG8_LAS unsigned*)(lds + (bufoff) + ldsw + _i * 8192), 16, 0, 0); } while (0)
; #define PG8_LDA(dst, b, h) do { _Pragma("unroll") for (int m = 0; m < 4; ++m) _Pragma("unroll") for (int k = 0; k < 2; ++k) dst[m][k] = *(const PG8_LAS bf16x8*)(lds + PG8_SA(b, h) + aoff + m * 2048 + k * 1024); } while (0)
; #define PG8_MMA(ai, bj, At, Bt) do { __builtin_amdgcn_s_setprio(1); _Pragma("unroll") for (int m = 0; m < 4; ++m) _Pragma("unroll") for (int n = 0; n < 2; ++n) _Pragma("unroll") for (int k = 0; k < 2; ++k) \
;         acc[ai][bj][m][n] = __builtin_amdgcn_mfma_f32_16x16x32_bf16(Bt[n][k], At[m][k], acc[ai][bj][m][n], 0, 0, 0); __builtin_amdgcn_s_setprio(0); } while (0)
; #define PG8_WAIT_V(n) asm volatile("s_waitcnt vmcnt(" #n ")" ::: "memory")
; #define PG8_WAIT_L(n) asm volatile("s_waitcnt lgkmcnt(" #n ")" ::: "memory")
; #define PG8_BAR __builtin_amdgcn_s_barrier()
; #define PG8_SCHED __builtin_amdgcn_sched_barrier(0)
; template <class Epi, class Sched, bool ALIGN_EPI = false, bool SP2 = false>
; __device__ __forceinline__ void gemm_phase(PG8_LAS unsigned char* lds, const Gemm g, const Sched& S, const Epi& E) {
;     ...
;             PG8_LDA(At, 1, 1); PG8_STAGE(PG8_SB(1, 0), b3, voffB); PG8_STAGE(PG8_SB(1, 1), b3 + hstep, voffB); PG8_STAGE(PG8_SA(1, 0), a3, voffA);
;             PG8_WAIT_V(8); PG8_WAIT_L(0); PG8_BAR; PG8_MMA(1, 0, At, B0); PG8_MMA(1, 1, At, B1); PG8_BAR; PG8_SCHED;
;     ...
;         if (!has_next) break;
; #pragma unroll
;         for (int a = 0; a < 2; ++a)
; #pragma unroll
;             for (int b = 0; b < 2; ++b)
; #pragma unroll
;                 for (int m = 0; m < 4; ++m)
; #pragma unroll
;                     for (int n = 0; n < 2; ++n) acc[a][b][m][n] = (f32x4){0.f, 0.f, 0.f, 0.f};
;         cur = nxt; cA = nA; cB = nB; ++ui;
	v_mfma_f32_16x16x32_bf16 v[64:67], v[182:185], v[218:221], v[64:67]
	s_setprio 0
	s_add_i32 s28, s52, s38
	v_lshl_add_u64 v[206:207], v[206:207], 0, s[14:15]
	s_mov_b32 m0, s28
	ds_read_b128 v[186:189], v152 offset:49152
	ds_read_b128 v[190:193], v152 offset:50176
	ds_read_b128 v[194:197], v152 offset:51200
	ds_read_b128 v[198:201], v152 offset:52224
	ds_read_b128 v[202:205], v152 offset:53248
	ds_read_b128 v[210:213], v152 offset:54272
	ds_read_b128 v[214:217], v152 offset:55296
	ds_read_b128 v[218:221], v152 offset:56320
	global_load_lds_dwordx4 v[206:207], off
	s_add_i32 m0, s28, 0x2000
	s_add_u32 s26, s26, 0x40080
	v_lshl_add_u64 v[206:207], v[222:223], 0, s[14:15]
	s_addc_u32 s27, s27, 0
	s_add_i32 s28, s53, s38
	global_load_lds_dwordx4 v[206:207], off
	v_lshl_add_u64 v[206:207], s[26:27], 0, v[130:131]
	s_mov_b32 m0, s28
	s_nop 0
	global_load_lds_dwordx4 v[206:207], off
	v_lshl_add_u64 v[206:207], s[26:27], 0, v[134:135]
	s_add_i32 m0, s28, 0x2000
	s_nop 0
	global_load_lds_dwordx4 v[206:207], off
	v_lshl_add_u64 v[206:207], v[224:225], 0, s[14:15]
	s_mov_b32 m0, s59
	s_nop 0
	global_load_lds_dwordx4 v[206:207], off
	v_lshl_add_u64 v[206:207], v[226:227], 0, s[14:15]
	s_mov_b32 m0, s60
	s_nop 0
	global_load_lds_dwordx4 v[206:207], off
	s_waitcnt vmcnt(8)
	s_waitcnt lgkmcnt(0)
	s_barrier
	s_setprio 1
	s_waitcnt lgkmcnt(0)
	v_mfma_f32_16x16x32_bf16 v[60:63], v[154:157], v[186:189], v[60:63]
	v_mfma_f32_16x16x32_bf16 v[56:59], v[162:165], v[186:189], v[56:59]
	v_mfma_f32_16x16x32_bf16 v[44:47], v[154:157], v[194:197], v[44:47]
	v_mfma_f32_16x16x32_bf16 v[40:43], v[162:165], v[194:197], v[40:43]
	v_mfma_f32_16x16x32_bf16 v[28:31], v[154:157], v[202:205], v[28:31]
	v_mfma_f32_16x16x32_bf16 v[24:27], v[162:165], v[202:205], v[24:27]
	v_mfma_f32_16x16x32_bf16 v[12:15], v[154:157], v[214:217], v[12:15]
	v_mfma_f32_16x16x32_bf16 v[8:11], v[162:165], v[214:217], v[8:11]
	v_mfma_f32_16x16x32_bf16 v[60:63], v[158:161], v[190:193], v[60:63]
	v_mfma_f32_16x16x32_bf16 v[56:59], v[166:169], v[190:193], v[56:59]
	v_mfma_f32_16x16x32_bf16 v[44:47], v[158:161], v[198:201], v[44:47]
	v_mfma_f32_16x16x32_bf16 v[40:43], v[166:169], v[198:201], v[40:43]
	v_mfma_f32_16x16x32_bf16 v[28:31], v[158:161], v[210:213], v[28:31]
	v_mfma_f32_16x16x32_bf16 v[24:27], v[166:169], v[210:213], v[24:27]
	v_mfma_f32_16x16x32_bf16 v[12:15], v[158:161], v[218:221], v[12:15]
	v_mfma_f32_16x16x32_bf16 v[8:11], v[166:169], v[218:221], v[8:11]
	s_setprio 0
	s_setprio 1
	v_mfma_f32_16x16x32_bf16 v[52:55], v[170:173], v[186:189], v[52:55]
	v_mfma_f32_16x16x32_bf16 v[48:51], v[178:181], v[186:189], v[48:51]
	v_mfma_f32_16x16x32_bf16 v[36:39], v[170:173], v[194:197], v[36:39]
	v_mfma_f32_16x16x32_bf16 v[32:35], v[178:181], v[194:197], v[32:35]
	v_mfma_f32_16x16x32_bf16 v[20:23], v[170:173], v[202:205], v[20:23]
	v_mfma_f32_16x16x32_bf16 v[16:19], v[178:181], v[202:205], v[16:19]
	v_mfma_f32_16x16x32_bf16 v[4:7], v[170:173], v[214:217], v[4:7]
	v_mfma_f32_16x16x32_bf16 v[0:3], v[178:181], v[214:217], v[0:3]
	v_mfma_f32_16x16x32_bf16 v[52:55], v[174:177], v[190:193], v[52:55]
	v_mfma_f32_16x16x32_bf16 v[48:51], v[182:185], v[190:193], v[48:51]
	v_mfma_f32_16x16x32_bf16 v[36:39], v[174:177], v[198:201], v[36:39]
	v_mfma_f32_16x16x32_bf16 v[32:35], v[182:185], v[198:201], v[32:35]
	v_mfma_f32_16x16x32_bf16 v[20:23], v[174:177], v[210:213], v[20:23]
	v_mfma_f32_16x16x32_bf16 v[16:19], v[182:185], v[210:213], v[16:19]
	v_mfma_f32_16x16x32_bf16 v[4:7], v[174:177], v[218:221], v[4:7]
	s_barrier
	v_mfma_f32_16x16x32_bf16 v[0:3], v[182:185], v[218:221], v[0:3]
	s_setprio 0
	s_add_i32 s70, s70, 2
	s_add_u32 s24, s24, 0x100
	s_addc_u32 s25, s25, 0
	s_cmp_gt_u32 s70, 13
	s_cbranch_scc0 .LBB0_1009
	s_add_u32 s24, s66, 0xffffff00
	s_addc_u32 s25, s67, -1
	s_andn2_b64 vcc, exec, s[6:7]
	s_cbranch_vccnz .LBB0_1012
	v_mov_b32_e32 v0, 0
	s_mov_b32 s61, s16
	s_mov_b32 s10, s18
	s_mov_b64 s[12:13], s[22:23]
	s_mov_b32 s62, s65
	v_mov_b32_e32 v1, v0
	v_mov_b64_e32 v[2:3], v[0:1]
	v_mov_b64_e32 v[4:5], v[0:1]
	v_mov_b64_e32 v[6:7], v[0:1]
	v_mov_b64_e32 v[8:9], v[0:1]
	v_mov_b64_e32 v[10:11], v[0:1]
	v_mov_b64_e32 v[12:13], v[0:1]
	v_mov_b64_e32 v[14:15], v[0:1]
	v_mov_b64_e32 v[16:17], v[0:1]
	v_mov_b64_e32 v[18:19], v[0:1]
	v_mov_b64_e32 v[20:21], v[0:1]
	v_mov_b64_e32 v[22:23], v[0:1]
	v_mov_b64_e32 v[24:25], v[0:1]
	v_mov_b64_e32 v[26:27], v[0:1]
	v_mov_b64_e32 v[28:29], v[0:1]
	v_mov_b64_e32 v[30:31], v[0:1]
	v_mov_b64_e32 v[32:33], v[0:1]
	v_mov_b64_e32 v[34:35], v[0:1]
	v_mov_b64_e32 v[36:37], v[0:1]
	v_mov_b64_e32 v[38:39], v[0:1]
	v_mov_b64_e32 v[40:41], v[0:1]
	v_mov_b64_e32 v[42:43], v[0:1]
	v_mov_b64_e32 v[44:45], v[0:1]
	v_mov_b64_e32 v[46:47], v[0:1]
	v_mov_b64_e32 v[48:49], v[0:1]
	v_mov_b64_e32 v[50:51], v[0:1]
	v_mov_b64_e32 v[52:53], v[0:1]
	v_mov_b64_e32 v[54:55], v[0:1]
	v_mov_b64_e32 v[56:57], v[0:1]
	v_mov_b64_e32 v[58:59], v[0:1]
	v_mov_b64_e32 v[60:61], v[0:1]
	v_mov_b64_e32 v[62:63], v[0:1]
	v_mov_b64_e32 v[64:65], v[0:1]
	v_mov_b64_e32 v[66:67], v[0:1]
	v_mov_b64_e32 v[68:69], v[0:1]
	v_mov_b64_e32 v[70:71], v[0:1]
	v_mov_b64_e32 v[72:73], v[0:1]
	v_mov_b64_e32 v[74:75], v[0:1]
	v_mov_b64_e32 v[76:77], v[0:1]
	v_mov_b64_e32 v[78:79], v[0:1]
	v_mov_b64_e32 v[80:81], v[0:1]
	v_mov_b64_e32 v[82:83], v[0:1]
	v_mov_b64_e32 v[84:85], v[0:1]
	v_mov_b64_e32 v[86:87], v[0:1]
	v_mov_b64_e32 v[88:89], v[0:1]
	v_mov_b64_e32 v[90:91], v[0:1]
	v_mov_b64_e32 v[92:93], v[0:1]
	v_mov_b64_e32 v[94:95], v[0:1]
	v_mov_b64_e32 v[96:97], v[0:1]
	v_mov_b64_e32 v[98:99], v[0:1]
	v_mov_b64_e32 v[100:101], v[0:1]
	v_mov_b64_e32 v[102:103], v[0:1]
	v_mov_b64_e32 v[104:105], v[0:1]
	v_mov_b64_e32 v[106:107], v[0:1]
	v_mov_b64_e32 v[108:109], v[0:1]
	v_mov_b64_e32 v[110:111], v[0:1]
	v_mov_b64_e32 v[112:113], v[0:1]
	v_mov_b64_e32 v[114:115], v[0:1]
	v_mov_b64_e32 v[116:117], v[0:1]
	v_mov_b64_e32 v[118:119], v[0:1]
	v_mov_b64_e32 v[120:121], v[0:1]
	v_mov_b64_e32 v[122:123], v[0:1]
	v_mov_b64_e32 v[124:125], v[0:1]
	v_mov_b64_e32 v[126:127], v[0:1]
	s_andn2_b64 vcc, exec, s[4:5]
	s_cbranch_vccnz .LBB0_1013
	s_branch .LBB0_1014

; #define PG8_STAGE(bufoff, gbase, voff) do { _Pragma("unroll") for (int _i = 0; _i < 2; ++_i) \
;         __builtin_amdgcn_global_load_lds((const unsigned*)((const char*)(gbase) + (voff)[_i]), (PG8_LAS unsigned*)(lds + (bufoff) + ldsw + _i * 8192), 16, 0, 0); } while (0)
; #define PG8_LDA(dst, b, h) do { _Pragma("unroll") for (int m = 0; m < 4; ++m) _Pragma("unroll") for (int k = 0; k < 2; ++k) dst[m][k] = *(const PG8_LAS bf16x8*)(lds + PG8_SA(b, h) + aoff + m * 2048 + k * 1024); } while (0)
; #define PG8_LDB(dst, b, h) do { _Pragma("unroll") for (int n = 0; n < 2; ++n) _Pragma("unroll") for (int k = 0; k < 2; ++k) dst[n][k] = *(const PG8_LAS bf16x8*)(lds + PG8_SB(b, h) + boff + n * 2048 + k * 1024); } while (0)
; #define PG8_MMA(ai, bj, At, Bt) do { __builtin_amdgcn_s_setprio(1); _Pragma("unroll") for (int m = 0; m < 4; ++m) _Pragma("unroll") for (int n = 0; n < 2; ++n) _Pragma("unroll") for (int k = 0; k < 2; ++k) \
;         acc[ai][bj][m][n] = __builtin_amdgcn_mfma_f32_16x16x32_bf16(Bt[n][k], At[m][k], acc[ai][bj][m][n], 0, 0, 0); __builtin_amdgcn_s_setprio(0); } while (0)
; #define PG8_WAIT_V(n) asm volatile("s_waitcnt vmcnt(" #n ")" ::: "memory")
; #define PG8_WAIT_L(n) asm volatile("s_waitcnt lgkmcnt(" #n ")" ::: "memory")
; #define PG8_BAR __builtin_amdgcn_s_barrier()
; #define PG8_SCHED __builtin_amdgcn_sched_barrier(0)
; template <class Epi, class Sched, bool ALIGN_EPI = false, bool SP2 = false>
; __device__ __forceinline__ void gemm_phase(PG8_LAS unsigned char* lds, const Gemm g, const Sched& S, const Epi& E) {
;     ...
;             PG8_LDB(B0, 0, 0); PG8_LDB(B1, 0, 1); PG8_SCHED; PG8_LDA(At, 0, 0); PG8_STAGE(PG8_SA(1, 1), a1 + hstep, voffA);
;             PG8_WAIT_V(8); PG8_WAIT_L(0); PG8_BAR; PG8_MMA(0, 0, At, B0); PG8_MMA(0, 1, At, B1); PG8_BAR; PG8_SCHED;
;             PG8_LDA(At, 0, 1); PG8_STAGE(PG8_SB(0, 0), b2, voffB); PG8_STAGE(PG8_SB(0, 1), b2 + hstep, voffB); PG8_STAGE(PG8_SA(0, 0), a2, voffA);
;             PG8_WAIT_V(8); PG8_WAIT_L(0); PG8_BAR; PG8_MMA(1, 0, At, B0); PG8_MMA(1, 1, At, B1); PG8_BAR; PG8_SCHED;
.LBB0_1101:
	v_add_u32_e32 v162, s61, v148
	v_add_u32_e32 v178, s62, v148
	s_add_u32 s26, s12, s24
	ds_read_b128 v[150:153], v162
	ds_read_b128 v[154:157], v162 offset:1024
	ds_read_b128 v[158:161], v162 offset:2048
	ds_read_b128 v[162:165], v162 offset:3072
	ds_read_b128 v[166:169], v178
	ds_read_b128 v[170:173], v178 offset:1024
	ds_read_b128 v[174:177], v178 offset:2048
	ds_read_b128 v[178:181], v178 offset:3072
	s_addc_u32 s27, s13, s25
	s_add_u32 s26, s26, 0x100
	s_addc_u32 s27, s27, 0
	s_add_u32 s52, s64, s24
	s_addc_u32 s53, s65, s25
	s_cmpk_eq_i32 s24, 0x700
	s_cselect_b32 s29, s19, s27
	s_cselect_b32 s28, s66, s26
	s_cselect_b32 s27, s17, s53
	s_cselect_b32 s26, s67, s52
	v_lshl_add_u64 v[206:207], v[140:141], 0, s[24:25]
	s_add_i32 m0, s11, 0xc000
	ds_read_b128 v[182:185], v149
	ds_read_b128 v[186:189], v149 offset:1024
	ds_read_b128 v[190:193], v149 offset:2048
	ds_read_b128 v[194:197], v149 offset:3072
	ds_read_b128 v[198:201], v149 offset:4096
	ds_read_b128 v[202:205], v149 offset:5120
	ds_read_b128 v[210:213], v149 offset:6144
	ds_read_b128 v[214:217], v149 offset:7168
	global_load_lds_dwordx4 v[206:207], off
	v_lshl_add_u64 v[206:207], v[142:143], 0, s[24:25]
	s_add_i32 m0, s11, 0xe000
	s_nop 0
	global_load_lds_dwordx4 v[206:207], off
	s_waitcnt vmcnt(8)
	s_waitcnt lgkmcnt(0)
	s_barrier
	s_setprio 1
	s_waitcnt lgkmcnt(0)
	v_mfma_f32_16x16x32_bf16 v[124:127], v[150:153], v[182:185], v[124:127]
	v_mfma_f32_16x16x32_bf16 v[120:123], v[158:161], v[182:185], v[120:123]
	v_mfma_f32_16x16x32_bf16 v[108:111], v[150:153], v[190:193], v[108:111]
	v_mfma_f32_16x16x32_bf16 v[104:107], v[158:161], v[190:193], v[104:107]
	v_mfma_f32_16x16x32_bf16 v[92:95], v[150:153], v[198:201], v[92:95]
	v_mfma_f32_16x16x32_bf16 v[88:91], v[158:161], v[198:201], v[88:91]
	v_mfma_f32_16x16x32_bf16 v[76:79], v[150:153], v[210:213], v[76:79]
	v_mfma_f32_16x16x32_bf16 v[72:75], v[158:161], v[210:213], v[72:75]
	v_mfma_f32_16x16x32_bf16 v[124:127], v[154:157], v[186:189], v[124:127]
	v_mfma_f32_16x16x32_bf16 v[120:123], v[162:165], v[186:189], v[120:123]
	v_mfma_f32_16x16x32_bf16 v[108:111], v[154:157], v[194:197], v[108:111]
	v_mfma_f32_16x16x32_bf16 v[104:107], v[162:165], v[194:197], v[104:107]
	v_mfma_f32_16x16x32_bf16 v[92:95], v[154:157], v[202:205], v[92:95]
	v_mfma_f32_16x16x32_bf16 v[88:91], v[162:165], v[202:205], v[88:91]
	v_mfma_f32_16x16x32_bf16 v[76:79], v[154:157], v[214:217], v[76:79]
	v_mfma_f32_16x16x32_bf16 v[72:75], v[162:165], v[214:217], v[72:75]
	s_setprio 0
	s_setprio 1
	v_mfma_f32_16x16x32_bf16 v[116:119], v[166:169], v[182:185], v[116:119]
	v_mfma_f32_16x16x32_bf16 v[112:115], v[174:177], v[182:185], v[112:115]
	v_mfma_f32_16x16x32_bf16 v[100:103], v[166:169], v[190:193], v[100:103]
	v_mfma_f32_16x16x32_bf16 v[96:99], v[174:177], v[190:193], v[96:99]
	v_mfma_f32_16x16x32_bf16 v[84:87], v[166:169], v[198:201], v[84:87]
	v_mfma_f32_16x16x32_bf16 v[80:83], v[174:177], v[198:201], v[80:83]
	v_mfma_f32_16x16x32_bf16 v[68:71], v[166:169], v[210:213], v[68:71]
	v_mfma_f32_16x16x32_bf16 v[64:67], v[174:177], v[210:213], v[64:67]
	v_mfma_f32_16x16x32_bf16 v[116:119], v[170:173], v[186:189], v[116:119]
	v_mfma_f32_16x16x32_bf16 v[112:115], v[178:181], v[186:189], v[112:115]
	v_mfma_f32_16x16x32_bf16 v[100:103], v[170:173], v[194:197], v[100:103]
	v_mfma_f32_16x16x32_bf16 v[96:99], v[178:181], v[194:197], v[96:99]
	v_mfma_f32_16x16x32_bf16 v[84:87], v[170:173], v[202:205], v[84:87]
	v_mfma_f32_16x16x32_bf16 v[80:83], v[178:181], v[202:205], v[80:83]
	v_mfma_f32_16x16x32_bf16 v[68:71], v[170:173], v[214:217], v[68:71]
	s_barrier
	v_mfma_f32_16x16x32_bf16 v[64:67], v[178:181], v[214:217], v[64:67]
	s_setprio 0
	s_add_i32 s52, s61, s37
	v_lshl_add_u64 v[206:207], s[26:27], 0, v[128:129]
	s_mov_b32 m0, s52
	ds_read_b128 v[182:185], v149 offset:16384
	ds_read_b128 v[186:189], v149 offset:17408
	ds_read_b128 v[190:193], v149 offset:18432
	ds_read_b128 v[194:197], v149 offset:19456
	ds_read_b128 v[198:201], v149 offset:20480
	ds_read_b128 v[202:205], v149 offset:21504
	ds_read_b128 v[210:213], v149 offset:22528
	ds_read_b128 v[214:217], v149 offset:23552
	global_load_lds_dwordx4 v[206:207], off
	s_add_i32 m0, s52, 0x2000
	s_add_u32 s52, s26, 0x40000
	v_lshl_add_u64 v[218:219], s[26:27], 0, v[130:131]
	s_addc_u32 s53, s27, 0
	s_add_i32 s69, s62, s37
	global_load_lds_dwordx4 v[218:219], off
	v_lshl_add_u64 v[220:221], s[52:53], 0, v[128:129]
	s_mov_b32 m0, s69
	v_lshl_add_u64 v[222:223], s[28:29], 0, v[130:131]
	global_load_lds_dwordx4 v[220:221], off
	v_lshl_add_u64 v[220:221], s[52:53], 0, v[130:131]
	s_add_i32 m0, s69, 0x2000
	s_nop 0
	global_load_lds_dwordx4 v[220:221], off
	v_lshl_add_u64 v[220:221], s[28:29], 0, v[128:129]
	s_mov_b32 m0, s11
	s_nop 0
	global_load_lds_dwordx4 v[220:221], off
	s_mov_b32 m0, s40
	s_nop 0
	global_load_lds_dwordx4 v[222:223], off
	s_waitcnt vmcnt(8)
	s_waitcnt lgkmcnt(0)
	s_barrier
; #define PG8_STAGE(bufoff, gbase, voff) do { _Pragma("unroll") for (int _i = 0; _i < 2; ++_i) \
;         __builtin_amdgcn_global_load_lds((const unsigned*)((const char*)(gbase) + (voff)[_i]), (PG8_LAS unsigned*)(lds + (bufoff) + ldsw + _i * 8192), 16, 0, 0); } while (0)
; #define PG8_LDA(dst, b, h) do { _Pragma("unroll") for (int m = 0; m < 4; ++m) _Pragma("unroll") for (int k = 0; k < 2; ++k) dst[m][k] = *(const PG8_LAS bf16x8*)(lds + PG8_SA(b, h) + aoff + m * 2048 + k * 1024); } while (0)
; #define PG8_LDB(dst, b, h) do { _Pragma("unroll") for (int n = 0; n < 2; ++n) _Pragma("unroll") for (int k = 0; k < 2; ++k) dst[n][k] = *(const PG8_LAS bf16x8*)(lds + PG8_SB(b, h) + boff + n * 2048 + k * 1024); } while (0)
; #define PG8_MMA(ai, bj, At, Bt) do { __builtin_amdgcn_s_setprio(1); _Pragma("unroll") for (int m = 0; m < 4; ++m) _Pragma("unroll") for (int n = 0; n < 2; ++n) _Pragma("unroll") for (int k = 0; k < 2; ++k) \
;         acc[ai][bj][m][n] = __builtin_amdgcn_mfma_f32_16x16x32_bf16(Bt[n][k], At[m][k], acc[ai][bj][m][n], 0, 0, 0); __builtin_amdgcn_s_setprio(0); } while (0)
; #define PG8_WAIT_V(n) asm volatile("s_waitcnt vmcnt(" #n ")" ::: "memory")
; #define PG8_WAIT_L(n) asm volatile("s_waitcnt lgkmcnt(" #n ")" ::: "memory")
; #define PG8_BAR __builtin_amdgcn_s_barrier()
; #define PG8_SCHED __builtin_amdgcn_sched_barrier(0)
; template <class Epi, class Sched, bool ALIGN_EPI = false, bool SP2 = false>
; __device__ __forceinline__ void gemm_phase(PG8_LAS unsigned char* lds, const Gemm g, const Sched& S, const Epi& E) {
;     ...
;             PG8_WAIT_V(8); PG8_WAIT_L(0); PG8_BAR; PG8_MMA(1, 0, At, B0); PG8_MMA(1, 1, At, B1); PG8_BAR; PG8_SCHED;
;             PG8_LDB(B0, 1, 0); PG8_LDB(B1, 1, 1); PG8_SCHED; PG8_LDA(At, 1, 0); PG8_STAGE(PG8_SA(0, 1), a2 + hstep, voffA);
;             PG8_WAIT_V(8); PG8_WAIT_L(0); PG8_BAR; PG8_MMA(0, 0, At, B0); PG8_MMA(0, 1, At, B1); PG8_BAR; PG8_SCHED;
	s_setprio 1
	s_waitcnt lgkmcnt(0)
	v_mfma_f32_16x16x32_bf16 v[60:63], v[150:153], v[182:185], v[60:63]
	v_mfma_f32_16x16x32_bf16 v[56:59], v[158:161], v[182:185], v[56:59]
	v_mfma_f32_16x16x32_bf16 v[44:47], v[150:153], v[190:193], v[44:47]
	v_mfma_f32_16x16x32_bf16 v[40:43], v[158:161], v[190:193], v[40:43]
	v_mfma_f32_16x16x32_bf16 v[28:31], v[150:153], v[198:201], v[28:31]
	v_mfma_f32_16x16x32_bf16 v[24:27], v[158:161], v[198:201], v[24:27]
	v_mfma_f32_16x16x32_bf16 v[12:15], v[150:153], v[210:213], v[12:15]
	v_mfma_f32_16x16x32_bf16 v[8:11], v[158:161], v[210:213], v[8:11]
	v_mfma_f32_16x16x32_bf16 v[60:63], v[154:157], v[186:189], v[60:63]
	v_mfma_f32_16x16x32_bf16 v[56:59], v[162:165], v[186:189], v[56:59]
	v_mfma_f32_16x16x32_bf16 v[44:47], v[154:157], v[194:197], v[44:47]
	v_mfma_f32_16x16x32_bf16 v[40:43], v[162:165], v[194:197], v[40:43]
	v_mfma_f32_16x16x32_bf16 v[28:31], v[154:157], v[202:205], v[28:31]
	v_mfma_f32_16x16x32_bf16 v[24:27], v[162:165], v[202:205], v[24:27]
	v_mfma_f32_16x16x32_bf16 v[12:15], v[154:157], v[214:217], v[12:15]
	v_mfma_f32_16x16x32_bf16 v[8:11], v[162:165], v[214:217], v[8:11]
	s_setprio 0
	s_setprio 1
	v_mfma_f32_16x16x32_bf16 v[52:55], v[166:169], v[182:185], v[52:55]
	v_mfma_f32_16x16x32_bf16 v[48:51], v[174:177], v[182:185], v[48:51]
	v_mfma_f32_16x16x32_bf16 v[36:39], v[166:169], v[190:193], v[36:39]
	v_mfma_f32_16x16x32_bf16 v[32:35], v[174:177], v[190:193], v[32:35]
	v_mfma_f32_16x16x32_bf16 v[20:23], v[166:169], v[198:201], v[20:23]
	v_mfma_f32_16x16x32_bf16 v[16:19], v[174:177], v[198:201], v[16:19]
	v_mfma_f32_16x16x32_bf16 v[4:7], v[166:169], v[210:213], v[4:7]
	v_mfma_f32_16x16x32_bf16 v[0:3], v[174:177], v[210:213], v[0:3]
	v_mfma_f32_16x16x32_bf16 v[52:55], v[170:173], v[186:189], v[52:55]
	v_mfma_f32_16x16x32_bf16 v[48:51], v[178:181], v[186:189], v[48:51]
	v_mfma_f32_16x16x32_bf16 v[36:39], v[170:173], v[194:197], v[36:39]
	v_mfma_f32_16x16x32_bf16 v[32:35], v[178:181], v[194:197], v[32:35]
	v_mfma_f32_16x16x32_bf16 v[20:23], v[170:173], v[202:205], v[20:23]
	v_mfma_f32_16x16x32_bf16 v[16:19], v[178:181], v[202:205], v[16:19]
	v_mfma_f32_16x16x32_bf16 v[4:7], v[170:173], v[214:217], v[4:7]
	s_barrier
	v_mfma_f32_16x16x32_bf16 v[0:3], v[178:181], v[214:217], v[0:3]
	s_setprio 0
	s_add_i32 s52, 0, 0x18000
	s_add_i32 s53, 0, 0x1c000
	v_add_u32_e32 v162, s52, v148
	v_add_u32_e32 v178, s53, v148
	ds_read_b128 v[150:153], v162
	ds_read_b128 v[154:157], v162 offset:1024
	ds_read_b128 v[158:161], v162 offset:2048
	ds_read_b128 v[162:165], v162 offset:3072
	ds_read_b128 v[166:169], v178
	ds_read_b128 v[170:173], v178 offset:1024
	ds_read_b128 v[174:177], v178 offset:2048
	ds_read_b128 v[178:181], v178 offset:3072
	s_add_u32 s28, s28, 0x40000
	s_addc_u32 s29, s29, 0
	s_mov_b32 m0, s41
	v_lshl_add_u64 v[224:225], s[28:29], 0, v[128:129]
	ds_read_b128 v[182:185], v149 offset:32768
	ds_read_b128 v[186:189], v149 offset:33792
	ds_read_b128 v[190:193], v149 offset:34816
	ds_read_b128 v[194:197], v149 offset:35840
	ds_read_b128 v[198:201], v149 offset:36864
	ds_read_b128 v[202:205], v149 offset:37888
	ds_read_b128 v[210:213], v149 offset:38912
	ds_read_b128 v[214:217], v149 offset:39936
	global_load_lds_dwordx4 v[224:225], off
	v_lshl_add_u64 v[224:225], s[28:29], 0, v[130:131]
	s_mov_b32 m0, s42
	s_nop 0
	global_load_lds_dwordx4 v[224:225], off
	s_waitcnt vmcnt(8)
	s_waitcnt lgkmcnt(0)
	s_barrier
	s_setprio 1
	s_waitcnt lgkmcnt(0)
	v_mfma_f32_16x16x32_bf16 v[124:127], v[150:153], v[182:185], v[124:127]
	v_mfma_f32_16x16x32_bf16 v[120:123], v[158:161], v[182:185], v[120:123]
	v_mfma_f32_16x16x32_bf16 v[108:111], v[150:153], v[190:193], v[108:111]
	v_mfma_f32_16x16x32_bf16 v[104:107], v[158:161], v[190:193], v[104:107]
	v_mfma_f32_16x16x32_bf16 v[92:95], v[150:153], v[198:201], v[92:95]
	v_mfma_f32_16x16x32_bf16 v[88:91], v[158:161], v[198:201], v[88:91]
	v_mfma_f32_16x16x32_bf16 v[76:79], v[150:153], v[210:213], v[76:79]
	v_mfma_f32_16x16x32_bf16 v[72:75], v[158:161], v[210:213], v[72:75]
	v_mfma_f32_16x16x32_bf16 v[124:127], v[154:157], v[186:189], v[124:127]
	v_mfma_f32_16x16x32_bf16 v[120:123], v[162:165], v[186:189], v[120:123]
	v_mfma_f32_16x16x32_bf16 v[108:111], v[154:157], v[194:197], v[108:111]
	v_mfma_f32_16x16x32_bf16 v[104:107], v[162:165], v[194:197], v[104:107]
	v_mfma_f32_16x16x32_bf16 v[92:95], v[154:157], v[202:205], v[92:95]
	v_mfma_f32_16x16x32_bf16 v[88:91], v[162:165], v[202:205], v[88:91]
	v_mfma_f32_16x16x32_bf16 v[76:79], v[154:157], v[214:217], v[76:79]
	v_mfma_f32_16x16x32_bf16 v[72:75], v[162:165], v[214:217], v[72:75]
	s_setprio 0
	s_setprio 1
	v_mfma_f32_16x16x32_bf16 v[116:119], v[166:169], v[182:185], v[116:119]
	v_mfma_f32_16x16x32_bf16 v[112:115], v[174:177], v[182:185], v[112:115]
	v_mfma_f32_16x16x32_bf16 v[100:103], v[166:169], v[190:193], v[100:103]
	v_mfma_f32_16x16x32_bf16 v[96:99], v[174:177], v[190:193], v[96:99]
	v_mfma_f32_16x16x32_bf16 v[84:87], v[166:169], v[198:201], v[84:87]
	v_mfma_f32_16x16x32_bf16 v[80:83], v[174:177], v[198:201], v[80:83]
	v_mfma_f32_16x16x32_bf16 v[68:71], v[166:169], v[210:213], v[68:71]
	v_mfma_f32_16x16x32_bf16 v[64:67], v[174:177], v[210:213], v[64:67]
	v_mfma_f32_16x16x32_bf16 v[116:119], v[170:173], v[186:189], v[116:119]
	v_mfma_f32_16x16x32_bf16 v[112:115], v[178:181], v[186:189], v[112:115]
	v_mfma_f32_16x16x32_bf16 v[100:103], v[170:173], v[194:197], v[100:103]
	v_mfma_f32_16x16x32_bf16 v[96:99], v[178:181], v[194:197], v[96:99]
	v_mfma_f32_16x16x32_bf16 v[84:87], v[170:173], v[202:205], v[84:87]
	v_mfma_f32_16x16x32_bf16 v[80:83], v[178:181], v[202:205], v[80:83]
	v_mfma_f32_16x16x32_bf16 v[68:71], v[170:173], v[214:217], v[68:71]
	s_barrier
; #define PG8_STAGE(bufoff, gbase, voff) do { _Pragma("unroll") for (int _i = 0; _i < 2; ++_i) \
;         __builtin_amdgcn_global_load_lds((const unsigned*)((const char*)(gbase) + (voff)[_i]), (PG8_LAS unsigned*)(lds + (bufoff) + ldsw + _i * 8192), 16, 0, 0); } while (0)
; #define PG8_LDA(dst, b, h) do { _Pragma("unroll") for (int m = 0; m < 4; ++m) _Pragma("unroll") for (int k = 0; k < 2; ++k) dst[m][k] = *(const PG8_LAS bf16x8*)(lds + PG8_SA(b, h) + aoff + m * 2048 + k * 1024); } while (0)
; #define PG8_MMA(ai, bj, At, Bt) do { __builtin_amdgcn_s_setprio(1); _Pragma("unroll") for (int m = 0; m < 4; ++m) _Pragma("unroll") for (int n = 0; n < 2; ++n) _Pragma("unroll") for (int k = 0; k < 2; ++k) \
;         acc[ai][bj][m][n] = __builtin_amdgcn_mfma_f32_16x16x32_bf16(Bt[n][k], At[m][k], acc[ai][bj][m][n], 0, 0, 0); __builtin_amdgcn_s_setprio(0); } while (0)
; #define PG8_WAIT_V(n) asm volatile("s_waitcnt vmcnt(" #n ")" ::: "memory")
; #define PG8_WAIT_L(n) asm volatile("s_waitcnt lgkmcnt(" #n ")" ::: "memory")
; #define PG8_BAR __builtin_amdgcn_s_barrier()
; #define PG8_SCHED __builtin_amdgcn_sched_barrier(0)
; template <class Epi, class Sched, bool ALIGN_EPI = false, bool SP2 = false>
; __device__ __forceinline__ void gemm_phase(PG8_LAS unsigned char* lds, const Gemm g, const Sched& S, const Epi& E) {
;     ...
;             PG8_LDA(At, 1, 1); PG8_STAGE(PG8_SB(1, 0), b3, voffB); PG8_STAGE(PG8_SB(1, 1), b3 + hstep, voffB); PG8_STAGE(PG8_SA(1, 0), a3, voffA);
;             PG8_WAIT_V(8); PG8_WAIT_L(0); PG8_BAR; PG8_MMA(1, 0, At, B0); PG8_MMA(1, 1, At, B1); PG8_BAR; PG8_SCHED;
;     ...
;         if (!has_next) break;
; #pragma unroll
;         for (int a = 0; a < 2; ++a)
; #pragma unroll
;             for (int b = 0; b < 2; ++b)
; #pragma unroll
;                 for (int m = 0; m < 4; ++m)
; #pragma unroll
;                     for (int n = 0; n < 2; ++n) acc[a][b][m][n] = (f32x4){0.f, 0.f, 0.f, 0.f};
;         cur = nxt; cA = nA; cB = nB; ++ui;
	v_mfma_f32_16x16x32_bf16 v[64:67], v[178:181], v[214:217], v[64:67]
	s_setprio 0
	s_add_i32 s28, s52, s37
	v_lshl_add_u64 v[206:207], v[206:207], 0, s[14:15]
	s_mov_b32 m0, s28
	ds_read_b128 v[182:185], v149 offset:49152
	ds_read_b128 v[186:189], v149 offset:50176
	ds_read_b128 v[190:193], v149 offset:51200
	ds_read_b128 v[194:197], v149 offset:52224
	ds_read_b128 v[198:201], v149 offset:53248
	ds_read_b128 v[202:205], v149 offset:54272
	ds_read_b128 v[210:213], v149 offset:55296
	ds_read_b128 v[214:217], v149 offset:56320
	global_load_lds_dwordx4 v[206:207], off
	s_add_i32 m0, s28, 0x2000
	s_add_u32 s26, s26, 0x40080
	v_lshl_add_u64 v[206:207], v[218:219], 0, s[14:15]
	s_addc_u32 s27, s27, 0
	s_add_i32 s28, s53, s37
	global_load_lds_dwordx4 v[206:207], off
	v_lshl_add_u64 v[206:207], s[26:27], 0, v[128:129]
	s_mov_b32 m0, s28
	s_nop 0
	global_load_lds_dwordx4 v[206:207], off
	v_lshl_add_u64 v[206:207], s[26:27], 0, v[130:131]
	s_add_i32 m0, s28, 0x2000
	s_nop 0
	global_load_lds_dwordx4 v[206:207], off
	v_lshl_add_u64 v[206:207], v[220:221], 0, s[14:15]
	s_mov_b32 m0, s59
	s_nop 0
	global_load_lds_dwordx4 v[206:207], off
	v_lshl_add_u64 v[206:207], v[222:223], 0, s[14:15]
	s_mov_b32 m0, s60
	s_nop 0
	global_load_lds_dwordx4 v[206:207], off
	s_waitcnt vmcnt(8)
	s_waitcnt lgkmcnt(0)
	s_barrier
	s_setprio 1
	s_waitcnt lgkmcnt(0)
	v_mfma_f32_16x16x32_bf16 v[60:63], v[150:153], v[182:185], v[60:63]
	v_mfma_f32_16x16x32_bf16 v[56:59], v[158:161], v[182:185], v[56:59]
	v_mfma_f32_16x16x32_bf16 v[44:47], v[150:153], v[190:193], v[44:47]
	v_mfma_f32_16x16x32_bf16 v[40:43], v[158:161], v[190:193], v[40:43]
	v_mfma_f32_16x16x32_bf16 v[28:31], v[150:153], v[198:201], v[28:31]
	v_mfma_f32_16x16x32_bf16 v[24:27], v[158:161], v[198:201], v[24:27]
	v_mfma_f32_16x16x32_bf16 v[12:15], v[150:153], v[210:213], v[12:15]
	v_mfma_f32_16x16x32_bf16 v[8:11], v[158:161], v[210:213], v[8:11]
	v_mfma_f32_16x16x32_bf16 v[60:63], v[154:157], v[186:189], v[60:63]
	v_mfma_f32_16x16x32_bf16 v[56:59], v[162:165], v[186:189], v[56:59]
	v_mfma_f32_16x16x32_bf16 v[44:47], v[154:157], v[194:197], v[44:47]
	v_mfma_f32_16x16x32_bf16 v[40:43], v[162:165], v[194:197], v[40:43]
	v_mfma_f32_16x16x32_bf16 v[28:31], v[154:157], v[202:205], v[28:31]
	v_mfma_f32_16x16x32_bf16 v[24:27], v[162:165], v[202:205], v[24:27]
	v_mfma_f32_16x16x32_bf16 v[12:15], v[154:157], v[214:217], v[12:15]
	v_mfma_f32_16x16x32_bf16 v[8:11], v[162:165], v[214:217], v[8:11]
	s_setprio 0
	s_setprio 1
	v_mfma_f32_16x16x32_bf16 v[52:55], v[166:169], v[182:185], v[52:55]
	v_mfma_f32_16x16x32_bf16 v[48:51], v[174:177], v[182:185], v[48:51]
	v_mfma_f32_16x16x32_bf16 v[36:39], v[166:169], v[190:193], v[36:39]
	v_mfma_f32_16x16x32_bf16 v[32:35], v[174:177], v[190:193], v[32:35]
	v_mfma_f32_16x16x32_bf16 v[20:23], v[166:169], v[198:201], v[20:23]
	v_mfma_f32_16x16x32_bf16 v[16:19], v[174:177], v[198:201], v[16:19]
	v_mfma_f32_16x16x32_bf16 v[4:7], v[166:169], v[210:213], v[4:7]
	v_mfma_f32_16x16x32_bf16 v[0:3], v[174:177], v[210:213], v[0:3]
	v_mfma_f32_16x16x32_bf16 v[52:55], v[170:173], v[186:189], v[52:55]
	v_mfma_f32_16x16x32_bf16 v[48:51], v[178:181], v[186:189], v[48:51]
	v_mfma_f32_16x16x32_bf16 v[36:39], v[170:173], v[194:197], v[36:39]
	v_mfma_f32_16x16x32_bf16 v[32:35], v[178:181], v[194:197], v[32:35]
	v_mfma_f32_16x16x32_bf16 v[20:23], v[170:173], v[202:205], v[20:23]
	v_mfma_f32_16x16x32_bf16 v[16:19], v[178:181], v[202:205], v[16:19]
	v_mfma_f32_16x16x32_bf16 v[4:7], v[170:173], v[214:217], v[4:7]
	s_barrier
	v_mfma_f32_16x16x32_bf16 v[0:3], v[178:181], v[214:217], v[0:3]
	s_setprio 0
	s_add_i32 s68, s68, 2
	s_add_u32 s24, s24, 0x100
	s_addc_u32 s25, s25, 0
	s_cmp_gt_u32 s68, 13
	s_cbranch_scc0 .LBB0_1101
	s_add_u32 s24, s64, 0xffffff00
	s_addc_u32 s25, s65, -1
	s_andn2_b64 vcc, exec, s[6:7]
	s_cbranch_vccnz .LBB0_1104
	v_mov_b32_e32 v0, 0
	s_mov_b32 s34, s16
	s_mov_b32 s10, s18
	s_mov_b64 s[12:13], s[22:23]
	s_mov_b32 s43, s63
	v_mov_b32_e32 v1, v0
	v_mov_b64_e32 v[2:3], v[0:1]
	v_mov_b64_e32 v[4:5], v[0:1]
	v_mov_b64_e32 v[6:7], v[0:1]
	v_mov_b64_e32 v[8:9], v[0:1]
	v_mov_b64_e32 v[10:11], v[0:1]
	v_mov_b64_e32 v[12:13], v[0:1]
	v_mov_b64_e32 v[14:15], v[0:1]
	v_mov_b64_e32 v[16:17], v[0:1]
	v_mov_b64_e32 v[18:19], v[0:1]
	v_mov_b64_e32 v[20:21], v[0:1]
	v_mov_b64_e32 v[22:23], v[0:1]
	v_mov_b64_e32 v[24:25], v[0:1]
	v_mov_b64_e32 v[26:27], v[0:1]
	v_mov_b64_e32 v[28:29], v[0:1]
	v_mov_b64_e32 v[30:31], v[0:1]
	v_mov_b64_e32 v[32:33], v[0:1]
	v_mov_b64_e32 v[34:35], v[0:1]
	v_mov_b64_e32 v[36:37], v[0:1]
	v_mov_b64_e32 v[38:39], v[0:1]
	v_mov_b64_e32 v[40:41], v[0:1]
	v_mov_b64_e32 v[42:43], v[0:1]
	v_mov_b64_e32 v[44:45], v[0:1]
	v_mov_b64_e32 v[46:47], v[0:1]
	v_mov_b64_e32 v[48:49], v[0:1]
	v_mov_b64_e32 v[50:51], v[0:1]
	v_mov_b64_e32 v[52:53], v[0:1]
	v_mov_b64_e32 v[54:55], v[0:1]
	v_mov_b64_e32 v[56:57], v[0:1]
	v_mov_b64_e32 v[58:59], v[0:1]
	v_mov_b64_e32 v[60:61], v[0:1]
	v_mov_b64_e32 v[62:63], v[0:1]
	v_mov_b64_e32 v[64:65], v[0:1]
	v_mov_b64_e32 v[66:67], v[0:1]
	v_mov_b64_e32 v[68:69], v[0:1]
	v_mov_b64_e32 v[70:71], v[0:1]
	v_mov_b64_e32 v[72:73], v[0:1]
	v_mov_b64_e32 v[74:75], v[0:1]
	v_mov_b64_e32 v[76:77], v[0:1]
	v_mov_b64_e32 v[78:79], v[0:1]
	v_mov_b64_e32 v[80:81], v[0:1]
	v_mov_b64_e32 v[82:83], v[0:1]
	v_mov_b64_e32 v[84:85], v[0:1]
	v_mov_b64_e32 v[86:87], v[0:1]
	v_mov_b64_e32 v[88:89], v[0:1]
	v_mov_b64_e32 v[90:91], v[0:1]
	v_mov_b64_e32 v[92:93], v[0:1]
	v_mov_b64_e32 v[94:95], v[0:1]
	v_mov_b64_e32 v[96:97], v[0:1]
	v_mov_b64_e32 v[98:99], v[0:1]
	v_mov_b64_e32 v[100:101], v[0:1]
	v_mov_b64_e32 v[102:103], v[0:1]
	v_mov_b64_e32 v[104:105], v[0:1]
	v_mov_b64_e32 v[106:107], v[0:1]
	v_mov_b64_e32 v[108:109], v[0:1]
	v_mov_b64_e32 v[110:111], v[0:1]
	v_mov_b64_e32 v[112:113], v[0:1]
	v_mov_b64_e32 v[114:115], v[0:1]
	v_mov_b64_e32 v[116:117], v[0:1]
	v_mov_b64_e32 v[118:119], v[0:1]
	v_mov_b64_e32 v[120:121], v[0:1]
	v_mov_b64_e32 v[122:123], v[0:1]
	v_mov_b64_e32 v[124:125], v[0:1]
	v_mov_b64_e32 v[126:127], v[0:1]
	s_andn2_b64 vcc, exec, s[4:5]
	s_cbranch_vccnz .LBB0_1105
	s_branch .LBB0_1106

; template <class Epi, class Sched, bool ALIGN_EPI = false, bool SP2 = false>
; __device__ __forceinline__ void gemm_phase(PG8_LAS unsigned char* lds, const Gemm g, const Sched& S, const Epi& E) {
;     ...
;         const bool has_next = S.next(ui + 1, nxt);
;         const char* nA = has_next ? (const char*)g.A + (size_t)nxt.pm * tstep : cA; const char* nB = has_next ? (const char*)g.Bt + (size_t)nxt.pn * tstep : cB;
;         for (int t = 0; t < nt; t += 2) {
;             const bool last = (t == nt - 2);
;             const char* a1 = cA + (size_t)(t + 1) * kstep;
;             const char* a2 = last ? nA : cA + (size_t)(t + 2) * kstep; const char* b2 = last ? nB : cB + (size_t)(t + 2) * kstep;
;             const char* a3 = a2 + kstep; const char* b3 = b2 + kstep;
;     ...
;         for (int a = 0; a < 2; ++a)
; #pragma unroll
;             for (int b = 0; b < 2; ++b)
; #pragma unroll
;                 for (int m = 0; m < 4; ++m)
; #pragma unroll
;                     for (int n = 0; n < 2; ++n) acc[a][b][m][n] = (f32x4){0.f, 0.f, 0.f, 0.f};
.LBB0_1270:
	s_ashr_i32 s27, s26, 31
	s_lshl_b64 s[28:29], s[26:27], 19
	s_add_u32 s28, s54, s28
	s_addc_u32 s29, s55, s29
	s_and_b64 s[30:31], s[4:5], exec
	s_cselect_b32 s27, s29, s35
	s_cselect_b32 s80, s28, s34
	s_ashr_i32 s25, s24, 31
	s_lshl_b64 s[30:31], s[24:25], 19
	s_add_u32 s30, s62, s30
	s_addc_u32 s31, s63, s31
	s_and_b64 s[38:39], s[4:5], exec
	s_cselect_b32 s25, s31, s37
	s_cselect_b32 s81, s30, s36
	s_add_u32 s34, s34, 0x40080
	s_addc_u32 s35, s35, 0
	s_add_u32 s82, s36, 0x100
	v_mov_b32_e32 v0, 0
	s_addc_u32 s83, s37, 0
	s_mov_b32 s84, -2
	v_mov_b32_e32 v1, v0
	v_mov_b64_e32 v[2:3], v[0:1]
	v_mov_b64_e32 v[4:5], v[0:1]
	v_mov_b64_e32 v[6:7], v[0:1]
	v_mov_b64_e32 v[8:9], v[0:1]
	v_mov_b64_e32 v[10:11], v[0:1]
	v_mov_b64_e32 v[12:13], v[0:1]
	v_mov_b64_e32 v[14:15], v[0:1]
	v_mov_b64_e32 v[16:17], v[0:1]
	v_mov_b64_e32 v[18:19], v[0:1]
	v_mov_b64_e32 v[20:21], v[0:1]
	v_mov_b64_e32 v[22:23], v[0:1]
	v_mov_b64_e32 v[24:25], v[0:1]
	v_mov_b64_e32 v[26:27], v[0:1]
	v_mov_b64_e32 v[28:29], v[0:1]
	v_mov_b64_e32 v[30:31], v[0:1]
	v_mov_b64_e32 v[32:33], v[0:1]
	v_mov_b64_e32 v[34:35], v[0:1]
	v_mov_b64_e32 v[36:37], v[0:1]
	v_mov_b64_e32 v[38:39], v[0:1]
	v_mov_b64_e32 v[40:41], v[0:1]
	v_mov_b64_e32 v[42:43], v[0:1]
	v_mov_b64_e32 v[44:45], v[0:1]
	v_mov_b64_e32 v[46:47], v[0:1]
	v_mov_b64_e32 v[48:49], v[0:1]
	v_mov_b64_e32 v[50:51], v[0:1]
	v_mov_b64_e32 v[52:53], v[0:1]
	v_mov_b64_e32 v[54:55], v[0:1]
	v_mov_b64_e32 v[56:57], v[0:1]
	v_mov_b64_e32 v[58:59], v[0:1]
	v_mov_b64_e32 v[60:61], v[0:1]
	v_mov_b64_e32 v[62:63], v[0:1]
	v_mov_b64_e32 v[64:65], v[0:1]
	v_mov_b64_e32 v[66:67], v[0:1]
	v_mov_b64_e32 v[68:69], v[0:1]
	v_mov_b64_e32 v[70:71], v[0:1]
	v_mov_b64_e32 v[72:73], v[0:1]
	v_mov_b64_e32 v[74:75], v[0:1]
	v_mov_b64_e32 v[76:77], v[0:1]
	v_mov_b64_e32 v[78:79], v[0:1]
	v_mov_b64_e32 v[80:81], v[0:1]
	v_mov_b64_e32 v[82:83], v[0:1]
	v_mov_b64_e32 v[84:85], v[0:1]
	v_mov_b64_e32 v[86:87], v[0:1]
	v_mov_b64_e32 v[88:89], v[0:1]
	v_mov_b64_e32 v[90:91], v[0:1]
	v_mov_b64_e32 v[92:93], v[0:1]
	v_mov_b64_e32 v[94:95], v[0:1]
	v_mov_b64_e32 v[96:97], v[0:1]
	v_mov_b64_e32 v[98:99], v[0:1]
	v_mov_b64_e32 v[100:101], v[0:1]
	v_mov_b64_e32 v[102:103], v[0:1]
	v_mov_b64_e32 v[104:105], v[0:1]
	v_mov_b64_e32 v[106:107], v[0:1]
	v_mov_b64_e32 v[108:109], v[0:1]
	v_mov_b64_e32 v[110:111], v[0:1]
	v_mov_b64_e32 v[112:113], v[0:1]
	v_mov_b64_e32 v[114:115], v[0:1]
	v_mov_b64_e32 v[116:117], v[0:1]
	v_mov_b64_e32 v[118:119], v[0:1]
	v_mov_b64_e32 v[120:121], v[0:1]
	v_mov_b64_e32 v[122:123], v[0:1]
	v_mov_b64_e32 v[124:125], v[0:1]
	v_mov_b64_e32 v[126:127], v[0:1]

; #define PG8_STAGE(bufoff, gbase, voff) do { _Pragma("unroll") for (int _i = 0; _i < 2; ++_i) \
;         __builtin_amdgcn_global_load_lds((const unsigned*)((const char*)(gbase) + (voff)[_i]), (PG8_LAS unsigned*)(lds + (bufoff) + ldsw + _i * 8192), 16, 0, 0); } while (0)
; #define PG8_LDA(dst, b, h) do { _Pragma("unroll") for (int m = 0; m < 4; ++m) _Pragma("unroll") for (int k = 0; k < 2; ++k) dst[m][k] = *(const PG8_LAS bf16x8*)(lds + PG8_SA(b, h) + aoff + m * 2048 + k * 1024); } while (0)
; #define PG8_LDB(dst, b, h) do { _Pragma("unroll") for (int n = 0; n < 2; ++n) _Pragma("unroll") for (int k = 0; k < 2; ++k) dst[n][k] = *(const PG8_LAS bf16x8*)(lds + PG8_SB(b, h) + boff + n * 2048 + k * 1024); } while (0)
; #define PG8_MMA(ai, bj, At, Bt) do { __builtin_amdgcn_s_setprio(1); _Pragma("unroll") for (int m = 0; m < 4; ++m) _Pragma("unroll") for (int n = 0; n < 2; ++n) _Pragma("unroll") for (int k = 0; k < 2; ++k) \
;         acc[ai][bj][m][n] = __builtin_amdgcn_mfma_f32_16x16x32_bf16(Bt[n][k], At[m][k], acc[ai][bj][m][n], 0, 0, 0); __builtin_amdgcn_s_setprio(0); } while (0)
; #define PG8_WAIT_V(n) asm volatile("s_waitcnt vmcnt(" #n ")" ::: "memory")
; #define PG8_WAIT_L(n) asm volatile("s_waitcnt lgkmcnt(" #n ")" ::: "memory")
; #define PG8_BAR __builtin_amdgcn_s_barrier()
; #define PG8_SCHED __builtin_amdgcn_sched_barrier(0)
; template <class Epi, class Sched, bool ALIGN_EPI = false, bool SP2 = false>
; __device__ __forceinline__ void gemm_phase(PG8_LAS unsigned char* lds, const Gemm g, const Sched& S, const Epi& E) {
;     ...
;             PG8_LDB(B0, 0, 0); PG8_LDB(B1, 0, 1); PG8_SCHED; PG8_LDA(At, 0, 0); PG8_STAGE(PG8_SA(1, 1), a1 + hstep, voffA);
;             PG8_WAIT_V(8); PG8_WAIT_L(0); PG8_BAR; PG8_MMA(0, 0, At, B0); PG8_MMA(0, 1, At, B1); PG8_BAR; PG8_SCHED;
;             PG8_LDA(At, 0, 1); PG8_STAGE(PG8_SB(0, 0), b2, voffB); PG8_STAGE(PG8_SB(0, 1), b2 + hstep, voffB); PG8_STAGE(PG8_SA(0, 0), a2, voffA);
;             PG8_WAIT_V(8); PG8_WAIT_L(0); PG8_BAR; PG8_MMA(1, 0, At, B0); PG8_MMA(1, 1, At, B1); PG8_BAR; PG8_SCHED;
.LBB0_1430:
	v_add_u32_e32 v153, s41, v151
	ds_read_b128 v[154:157], v153
	ds_read_b128 v[158:161], v153 offset:1024
	ds_read_b128 v[162:165], v153 offset:2048
	ds_read_b128 v[166:169], v153 offset:3072
	v_add_u32_e32 v153, s42, v151
	s_add_u32 s20, s12, s18
	ds_read_b128 v[170:173], v153
	ds_read_b128 v[174:177], v153 offset:1024
	ds_read_b128 v[178:181], v153 offset:2048
	ds_read_b128 v[182:185], v153 offset:3072
	s_addc_u32 s21, s13, s19
	s_add_u32 s20, s20, 0x100
	s_addc_u32 s21, s21, 0
	s_add_u32 s51, s46, s18
	s_addc_u32 s52, s47, s19
	s_cmpk_eq_i32 s18, 0x1500
	s_cselect_b32 s23, s17, s21
	s_cselect_b32 s22, s16, s20
	s_cselect_b32 s21, s5, s52
	s_cselect_b32 s20, s4, s51
	v_lshl_add_u64 v[206:207], v[144:145], 0, s[18:19]
	s_add_i32 m0, s31, 0xc000
	ds_read_b128 v[186:189], v152
	ds_read_b128 v[190:193], v152 offset:1024
	ds_read_b128 v[194:197], v152 offset:2048
	ds_read_b128 v[198:201], v152 offset:3072
	ds_read_b128 v[202:205], v152 offset:4096
	ds_read_b128 v[210:213], v152 offset:5120
	ds_read_b128 v[214:217], v152 offset:6144
	ds_read_b128 v[218:221], v152 offset:7168
	global_load_lds_dwordx4 v[206:207], off
	v_lshl_add_u64 v[206:207], v[146:147], 0, s[18:19]
	s_add_i32 m0, s31, 0xe000
	s_nop 0
	global_load_lds_dwordx4 v[206:207], off
	s_waitcnt vmcnt(8)
	s_waitcnt lgkmcnt(0)
	s_barrier
	s_setprio 1
	s_waitcnt lgkmcnt(0)
	v_mfma_f32_16x16x32_bf16 v[124:127], v[154:157], v[186:189], v[124:127]
	v_mfma_f32_16x16x32_bf16 v[120:123], v[162:165], v[186:189], v[120:123]
	v_mfma_f32_16x16x32_bf16 v[108:111], v[154:157], v[194:197], v[108:111]
	v_mfma_f32_16x16x32_bf16 v[104:107], v[162:165], v[194:197], v[104:107]
	v_mfma_f32_16x16x32_bf16 v[92:95], v[154:157], v[202:205], v[92:95]
	v_mfma_f32_16x16x32_bf16 v[88:91], v[162:165], v[202:205], v[88:91]
	v_mfma_f32_16x16x32_bf16 v[76:79], v[154:157], v[214:217], v[76:79]
	v_mfma_f32_16x16x32_bf16 v[72:75], v[162:165], v[214:217], v[72:75]
	v_mfma_f32_16x16x32_bf16 v[124:127], v[158:161], v[190:193], v[124:127]
	v_mfma_f32_16x16x32_bf16 v[120:123], v[166:169], v[190:193], v[120:123]
	v_mfma_f32_16x16x32_bf16 v[108:111], v[158:161], v[198:201], v[108:111]
	v_mfma_f32_16x16x32_bf16 v[104:107], v[166:169], v[198:201], v[104:107]
	v_mfma_f32_16x16x32_bf16 v[92:95], v[158:161], v[210:213], v[92:95]
	v_mfma_f32_16x16x32_bf16 v[88:91], v[166:169], v[210:213], v[88:91]
	v_mfma_f32_16x16x32_bf16 v[76:79], v[158:161], v[218:221], v[76:79]
	v_mfma_f32_16x16x32_bf16 v[72:75], v[166:169], v[218:221], v[72:75]
	s_setprio 0
	s_setprio 1
	v_mfma_f32_16x16x32_bf16 v[116:119], v[170:173], v[186:189], v[116:119]
	v_mfma_f32_16x16x32_bf16 v[112:115], v[178:181], v[186:189], v[112:115]
	v_mfma_f32_16x16x32_bf16 v[100:103], v[170:173], v[194:197], v[100:103]
	v_mfma_f32_16x16x32_bf16 v[96:99], v[178:181], v[194:197], v[96:99]
	v_mfma_f32_16x16x32_bf16 v[84:87], v[170:173], v[202:205], v[84:87]
	v_mfma_f32_16x16x32_bf16 v[80:83], v[178:181], v[202:205], v[80:83]
	v_mfma_f32_16x16x32_bf16 v[68:71], v[170:173], v[214:217], v[68:71]
	v_mfma_f32_16x16x32_bf16 v[64:67], v[178:181], v[214:217], v[64:67]
	v_mfma_f32_16x16x32_bf16 v[116:119], v[174:177], v[190:193], v[116:119]
	v_mfma_f32_16x16x32_bf16 v[112:115], v[182:185], v[190:193], v[112:115]
	v_mfma_f32_16x16x32_bf16 v[100:103], v[174:177], v[198:201], v[100:103]
	v_mfma_f32_16x16x32_bf16 v[96:99], v[182:185], v[198:201], v[96:99]
	v_mfma_f32_16x16x32_bf16 v[84:87], v[174:177], v[210:213], v[84:87]
	v_mfma_f32_16x16x32_bf16 v[80:83], v[182:185], v[210:213], v[80:83]
	v_mfma_f32_16x16x32_bf16 v[68:71], v[174:177], v[218:221], v[68:71]
	s_barrier
	v_mfma_f32_16x16x32_bf16 v[64:67], v[182:185], v[218:221], v[64:67]
	s_setprio 0
	s_add_i32 s51, s41, s30
	v_lshl_add_u64 v[206:207], s[20:21], 0, v[130:131]
	s_mov_b32 m0, s51
	ds_read_b128 v[186:189], v152 offset:16384
	ds_read_b128 v[190:193], v152 offset:17408
	ds_read_b128 v[194:197], v152 offset:18432
	ds_read_b128 v[198:201], v152 offset:19456
	ds_read_b128 v[202:205], v152 offset:20480
	ds_read_b128 v[210:213], v152 offset:21504
	ds_read_b128 v[214:217], v152 offset:22528
	ds_read_b128 v[218:221], v152 offset:23552
	global_load_lds_dwordx4 v[206:207], off
	s_add_i32 m0, s51, 0x2000
	s_add_u32 s52, s20, 0xb0000
	v_lshl_add_u64 v[222:223], s[20:21], 0, v[134:135]
	s_addc_u32 s53, s21, 0
	s_add_i32 s51, s42, s30
	global_load_lds_dwordx4 v[222:223], off
	v_lshl_add_u64 v[224:225], s[52:53], 0, v[130:131]
	s_mov_b32 m0, s51
	v_lshl_add_u64 v[226:227], s[22:23], 0, v[132:133]
	global_load_lds_dwordx4 v[224:225], off
	v_lshl_add_u64 v[224:225], s[52:53], 0, v[134:135]
	s_add_i32 m0, s51, 0x2000
	s_nop 0
	global_load_lds_dwordx4 v[224:225], off
	v_lshl_add_u64 v[224:225], s[22:23], 0, v[128:129]
	s_mov_b32 m0, s31
	s_nop 0
	global_load_lds_dwordx4 v[224:225], off
	s_mov_b32 m0, s33
	s_nop 0
	global_load_lds_dwordx4 v[226:227], off
	s_waitcnt vmcnt(8)
	s_waitcnt lgkmcnt(0)
	s_barrier
; #define PG8_STAGE(bufoff, gbase, voff) do { _Pragma("unroll") for (int _i = 0; _i < 2; ++_i) \
;         __builtin_amdgcn_global_load_lds((const unsigned*)((const char*)(gbase) + (voff)[_i]), (PG8_LAS unsigned*)(lds + (bufoff) + ldsw + _i * 8192), 16, 0, 0); } while (0)
; #define PG8_LDA(dst, b, h) do { _Pragma("unroll") for (int m = 0; m < 4; ++m) _Pragma("unroll") for (int k = 0; k < 2; ++k) dst[m][k] = *(const PG8_LAS bf16x8*)(lds + PG8_SA(b, h) + aoff + m * 2048 + k * 1024); } while (0)
; #define PG8_LDB(dst, b, h) do { _Pragma("unroll") for (int n = 0; n < 2; ++n) _Pragma("unroll") for (int k = 0; k < 2; ++k) dst[n][k] = *(const PG8_LAS bf16x8*)(lds + PG8_SB(b, h) + boff + n * 2048 + k * 1024); } while (0)
; #define PG8_MMA(ai, bj, At, Bt) do { __builtin_amdgcn_s_setprio(1); _Pragma("unroll") for (int m = 0; m < 4; ++m) _Pragma("unroll") for (int n = 0; n < 2; ++n) _Pragma("unroll") for (int k = 0; k < 2; ++k) \
;         acc[ai][bj][m][n] = __builtin_amdgcn_mfma_f32_16x16x32_bf16(Bt[n][k], At[m][k], acc[ai][bj][m][n], 0, 0, 0); __builtin_amdgcn_s_setprio(0); } while (0)
; #define PG8_WAIT_V(n) asm volatile("s_waitcnt vmcnt(" #n ")" ::: "memory")
; #define PG8_WAIT_L(n) asm volatile("s_waitcnt lgkmcnt(" #n ")" ::: "memory")
; #define PG8_BAR __builtin_amdgcn_s_barrier()
; #define PG8_SCHED __builtin_amdgcn_sched_barrier(0)
; template <class Epi, class Sched, bool ALIGN_EPI = false, bool SP2 = false>
; __device__ __forceinline__ void gemm_phase(PG8_LAS unsigned char* lds, const Gemm g, const Sched& S, const Epi& E) {
;     ...
;             PG8_WAIT_V(8); PG8_WAIT_L(0); PG8_BAR; PG8_MMA(1, 0, At, B0); PG8_MMA(1, 1, At, B1); PG8_BAR; PG8_SCHED;
;             PG8_LDB(B0, 1, 0); PG8_LDB(B1, 1, 1); PG8_SCHED; PG8_LDA(At, 1, 0); PG8_STAGE(PG8_SA(0, 1), a2 + hstep, voffA);
;             PG8_WAIT_V(8); PG8_WAIT_L(0); PG8_BAR; PG8_MMA(0, 0, At, B0); PG8_MMA(0, 1, At, B1); PG8_BAR; PG8_SCHED;
	s_setprio 1
	s_waitcnt lgkmcnt(0)
	v_mfma_f32_16x16x32_bf16 v[60:63], v[154:157], v[186:189], v[60:63]
	v_mfma_f32_16x16x32_bf16 v[56:59], v[162:165], v[186:189], v[56:59]
	v_mfma_f32_16x16x32_bf16 v[44:47], v[154:157], v[194:197], v[44:47]
	v_mfma_f32_16x16x32_bf16 v[40:43], v[162:165], v[194:197], v[40:43]
	v_mfma_f32_16x16x32_bf16 v[28:31], v[154:157], v[202:205], v[28:31]
	v_mfma_f32_16x16x32_bf16 v[24:27], v[162:165], v[202:205], v[24:27]
	v_mfma_f32_16x16x32_bf16 v[12:15], v[154:157], v[214:217], v[12:15]
	v_mfma_f32_16x16x32_bf16 v[8:11], v[162:165], v[214:217], v[8:11]
	v_mfma_f32_16x16x32_bf16 v[60:63], v[158:161], v[190:193], v[60:63]
	v_mfma_f32_16x16x32_bf16 v[56:59], v[166:169], v[190:193], v[56:59]
	v_mfma_f32_16x16x32_bf16 v[44:47], v[158:161], v[198:201], v[44:47]
	v_mfma_f32_16x16x32_bf16 v[40:43], v[166:169], v[198:201], v[40:43]
	v_mfma_f32_16x16x32_bf16 v[28:31], v[158:161], v[210:213], v[28:31]
	v_mfma_f32_16x16x32_bf16 v[24:27], v[166:169], v[210:213], v[24:27]
	v_mfma_f32_16x16x32_bf16 v[12:15], v[158:161], v[218:221], v[12:15]
	v_mfma_f32_16x16x32_bf16 v[8:11], v[166:169], v[218:221], v[8:11]
	s_setprio 0
	s_setprio 1
	v_mfma_f32_16x16x32_bf16 v[52:55], v[170:173], v[186:189], v[52:55]
	v_mfma_f32_16x16x32_bf16 v[48:51], v[178:181], v[186:189], v[48:51]
	v_mfma_f32_16x16x32_bf16 v[36:39], v[170:173], v[194:197], v[36:39]
	v_mfma_f32_16x16x32_bf16 v[32:35], v[178:181], v[194:197], v[32:35]
	v_mfma_f32_16x16x32_bf16 v[20:23], v[170:173], v[202:205], v[20:23]
	v_mfma_f32_16x16x32_bf16 v[16:19], v[178:181], v[202:205], v[16:19]
	v_mfma_f32_16x16x32_bf16 v[4:7], v[170:173], v[214:217], v[4:7]
	v_mfma_f32_16x16x32_bf16 v[0:3], v[178:181], v[214:217], v[0:3]
	v_mfma_f32_16x16x32_bf16 v[52:55], v[174:177], v[190:193], v[52:55]
	v_mfma_f32_16x16x32_bf16 v[48:51], v[182:185], v[190:193], v[48:51]
	v_mfma_f32_16x16x32_bf16 v[36:39], v[174:177], v[198:201], v[36:39]
	v_mfma_f32_16x16x32_bf16 v[32:35], v[182:185], v[198:201], v[32:35]
	v_mfma_f32_16x16x32_bf16 v[20:23], v[174:177], v[210:213], v[20:23]
	v_mfma_f32_16x16x32_bf16 v[16:19], v[182:185], v[210:213], v[16:19]
	v_mfma_f32_16x16x32_bf16 v[4:7], v[174:177], v[218:221], v[4:7]
	s_barrier
	v_mfma_f32_16x16x32_bf16 v[0:3], v[182:185], v[218:221], v[0:3]
	s_setprio 0
	s_add_i32 s51, 0, 0x18000
	v_add_u32_e32 v153, s51, v151
	s_add_i32 s52, 0, 0x1c000
	ds_read_b128 v[154:157], v153
	ds_read_b128 v[158:161], v153 offset:1024
	ds_read_b128 v[162:165], v153 offset:2048
	ds_read_b128 v[166:169], v153 offset:3072
	v_add_u32_e32 v153, s52, v151
	ds_read_b128 v[170:173], v153
	ds_read_b128 v[174:177], v153 offset:1024
	ds_read_b128 v[178:181], v153 offset:2048
	ds_read_b128 v[182:185], v153 offset:3072
	s_add_u32 s22, s22, 0xb0000
	s_addc_u32 s23, s23, 0
	s_mov_b32 m0, s34
	v_lshl_add_u64 v[228:229], s[22:23], 0, v[128:129]
	ds_read_b128 v[186:189], v152 offset:32768
	ds_read_b128 v[190:193], v152 offset:33792
	ds_read_b128 v[194:197], v152 offset:34816
	ds_read_b128 v[198:201], v152 offset:35840
	ds_read_b128 v[202:205], v152 offset:36864
	ds_read_b128 v[210:213], v152 offset:37888
	ds_read_b128 v[214:217], v152 offset:38912
	ds_read_b128 v[218:221], v152 offset:39936
	global_load_lds_dwordx4 v[228:229], off
	v_lshl_add_u64 v[228:229], s[22:23], 0, v[132:133]
	s_mov_b32 m0, s35
	s_nop 0
	global_load_lds_dwordx4 v[228:229], off
	s_waitcnt vmcnt(8)
	s_waitcnt lgkmcnt(0)
	s_barrier
	s_setprio 1
	s_waitcnt lgkmcnt(0)
	v_mfma_f32_16x16x32_bf16 v[124:127], v[154:157], v[186:189], v[124:127]
	v_mfma_f32_16x16x32_bf16 v[120:123], v[162:165], v[186:189], v[120:123]
	v_mfma_f32_16x16x32_bf16 v[108:111], v[154:157], v[194:197], v[108:111]
	v_mfma_f32_16x16x32_bf16 v[104:107], v[162:165], v[194:197], v[104:107]
	v_mfma_f32_16x16x32_bf16 v[92:95], v[154:157], v[202:205], v[92:95]
	v_mfma_f32_16x16x32_bf16 v[88:91], v[162:165], v[202:205], v[88:91]
	v_mfma_f32_16x16x32_bf16 v[76:79], v[154:157], v[214:217], v[76:79]
	v_mfma_f32_16x16x32_bf16 v[72:75], v[162:165], v[214:217], v[72:75]
	v_mfma_f32_16x16x32_bf16 v[124:127], v[158:161], v[190:193], v[124:127]
	v_mfma_f32_16x16x32_bf16 v[120:123], v[166:169], v[190:193], v[120:123]
	v_mfma_f32_16x16x32_bf16 v[108:111], v[158:161], v[198:201], v[108:111]
	v_mfma_f32_16x16x32_bf16 v[104:107], v[166:169], v[198:201], v[104:107]
	v_mfma_f32_16x16x32_bf16 v[92:95], v[158:161], v[210:213], v[92:95]
	v_mfma_f32_16x16x32_bf16 v[88:91], v[166:169], v[210:213], v[88:91]
	v_mfma_f32_16x16x32_bf16 v[76:79], v[158:161], v[218:221], v[76:79]
	v_mfma_f32_16x16x32_bf16 v[72:75], v[166:169], v[218:221], v[72:75]
	s_setprio 0
	s_setprio 1
	v_mfma_f32_16x16x32_bf16 v[116:119], v[170:173], v[186:189], v[116:119]
	v_mfma_f32_16x16x32_bf16 v[112:115], v[178:181], v[186:189], v[112:115]
	v_mfma_f32_16x16x32_bf16 v[100:103], v[170:173], v[194:197], v[100:103]
	v_mfma_f32_16x16x32_bf16 v[96:99], v[178:181], v[194:197], v[96:99]
	v_mfma_f32_16x16x32_bf16 v[84:87], v[170:173], v[202:205], v[84:87]
	v_mfma_f32_16x16x32_bf16 v[80:83], v[178:181], v[202:205], v[80:83]
	v_mfma_f32_16x16x32_bf16 v[68:71], v[170:173], v[214:217], v[68:71]
	v_mfma_f32_16x16x32_bf16 v[64:67], v[178:181], v[214:217], v[64:67]
	v_mfma_f32_16x16x32_bf16 v[116:119], v[174:177], v[190:193], v[116:119]
	v_mfma_f32_16x16x32_bf16 v[112:115], v[182:185], v[190:193], v[112:115]
	v_mfma_f32_16x16x32_bf16 v[100:103], v[174:177], v[198:201], v[100:103]
	v_mfma_f32_16x16x32_bf16 v[96:99], v[182:185], v[198:201], v[96:99]
	v_mfma_f32_16x16x32_bf16 v[84:87], v[174:177], v[210:213], v[84:87]
	v_mfma_f32_16x16x32_bf16 v[80:83], v[182:185], v[210:213], v[80:83]
	v_mfma_f32_16x16x32_bf16 v[68:71], v[174:177], v[218:221], v[68:71]
	s_barrier
; #define PG8_STAGE(bufoff, gbase, voff) do { _Pragma("unroll") for (int _i = 0; _i < 2; ++_i) \
;         __builtin_amdgcn_global_load_lds((const unsigned*)((const char*)(gbase) + (voff)[_i]), (PG8_LAS unsigned*)(lds + (bufoff) + ldsw + _i * 8192), 16, 0, 0); } while (0)
; #define PG8_LDA(dst, b, h) do { _Pragma("unroll") for (int m = 0; m < 4; ++m) _Pragma("unroll") for (int k = 0; k < 2; ++k) dst[m][k] = *(const PG8_LAS bf16x8*)(lds + PG8_SA(b, h) + aoff + m * 2048 + k * 1024); } while (0)
; #define PG8_MMA(ai, bj, At, Bt) do { __builtin_amdgcn_s_setprio(1); _Pragma("unroll") for (int m = 0; m < 4; ++m) _Pragma("unroll") for (int n = 0; n < 2; ++n) _Pragma("unroll") for (int k = 0; k < 2; ++k) \
;         acc[ai][bj][m][n] = __builtin_amdgcn_mfma_f32_16x16x32_bf16(Bt[n][k], At[m][k], acc[ai][bj][m][n], 0, 0, 0); __builtin_amdgcn_s_setprio(0); } while (0)
; #define PG8_WAIT_V(n) asm volatile("s_waitcnt vmcnt(" #n ")" ::: "memory")
; #define PG8_WAIT_L(n) asm volatile("s_waitcnt lgkmcnt(" #n ")" ::: "memory")
; #define PG8_BAR __builtin_amdgcn_s_barrier()
; #define PG8_SCHED __builtin_amdgcn_sched_barrier(0)
; template <class Epi, class Sched, bool ALIGN_EPI = false, bool SP2 = false>
; __device__ __forceinline__ void gemm_phase(PG8_LAS unsigned char* lds, const Gemm g, const Sched& S, const Epi& E) {
;     ...
;             PG8_LDA(At, 1, 1); PG8_STAGE(PG8_SB(1, 0), b3, voffB); PG8_STAGE(PG8_SB(1, 1), b3 + hstep, voffB); PG8_STAGE(PG8_SA(1, 0), a3, voffA);
;             PG8_WAIT_V(8); PG8_WAIT_L(0); PG8_BAR; PG8_MMA(1, 0, At, B0); PG8_MMA(1, 1, At, B1); PG8_BAR; PG8_SCHED;
;     ...
; #pragma unroll
;         for (int a = 0; a < 2; ++a)
; #pragma unroll
;             for (int b = 0; b < 2; ++b)
; #pragma unroll
;                 for (int m = 0; m < 4; ++m)
; #pragma unroll
;                     for (int n = 0; n < 2; ++n) acc[a][b][m][n] = (f32x4){0.f, 0.f, 0.f, 0.f};
;         cur = nxt; cA = nA; cB = nB; ++ui;
	v_mfma_f32_16x16x32_bf16 v[64:67], v[182:185], v[218:221], v[64:67]
	s_setprio 0
	s_add_i32 s22, s51, s30
	v_lshl_add_u64 v[206:207], v[206:207], 0, s[14:15]
	s_mov_b32 m0, s22
	ds_read_b128 v[186:189], v152 offset:49152
	ds_read_b128 v[190:193], v152 offset:50176
	ds_read_b128 v[194:197], v152 offset:51200
	ds_read_b128 v[198:201], v152 offset:52224
	ds_read_b128 v[202:205], v152 offset:53248
	ds_read_b128 v[210:213], v152 offset:54272
	ds_read_b128 v[214:217], v152 offset:55296
	ds_read_b128 v[218:221], v152 offset:56320
	global_load_lds_dwordx4 v[206:207], off
	s_add_i32 m0, s22, 0x2000
	s_add_u32 s20, s20, 0xb0080
	v_lshl_add_u64 v[206:207], v[222:223], 0, s[14:15]
	s_addc_u32 s21, s21, 0
	s_add_i32 s22, s52, s30
	global_load_lds_dwordx4 v[206:207], off
	v_lshl_add_u64 v[206:207], s[20:21], 0, v[130:131]
	s_mov_b32 m0, s22
	s_nop 0
	global_load_lds_dwordx4 v[206:207], off
	v_lshl_add_u64 v[206:207], s[20:21], 0, v[134:135]
	s_add_i32 m0, s22, 0x2000
	s_nop 0
	global_load_lds_dwordx4 v[206:207], off
	v_lshl_add_u64 v[206:207], v[224:225], 0, s[14:15]
	s_mov_b32 m0, s37
	s_nop 0
	global_load_lds_dwordx4 v[206:207], off
	v_lshl_add_u64 v[206:207], v[226:227], 0, s[14:15]
	s_mov_b32 m0, s38
	s_nop 0
	global_load_lds_dwordx4 v[206:207], off
	s_waitcnt vmcnt(8)
	s_waitcnt lgkmcnt(0)
	s_barrier
	s_setprio 1
	s_waitcnt lgkmcnt(0)
	v_mfma_f32_16x16x32_bf16 v[60:63], v[154:157], v[186:189], v[60:63]
	v_mfma_f32_16x16x32_bf16 v[56:59], v[162:165], v[186:189], v[56:59]
	v_mfma_f32_16x16x32_bf16 v[44:47], v[154:157], v[194:197], v[44:47]
	v_mfma_f32_16x16x32_bf16 v[40:43], v[162:165], v[194:197], v[40:43]
	v_mfma_f32_16x16x32_bf16 v[28:31], v[154:157], v[202:205], v[28:31]
	v_mfma_f32_16x16x32_bf16 v[24:27], v[162:165], v[202:205], v[24:27]
	v_mfma_f32_16x16x32_bf16 v[12:15], v[154:157], v[214:217], v[12:15]
	v_mfma_f32_16x16x32_bf16 v[8:11], v[162:165], v[214:217], v[8:11]
	v_mfma_f32_16x16x32_bf16 v[60:63], v[158:161], v[190:193], v[60:63]
	v_mfma_f32_16x16x32_bf16 v[56:59], v[166:169], v[190:193], v[56:59]
	v_mfma_f32_16x16x32_bf16 v[44:47], v[158:161], v[198:201], v[44:47]
	v_mfma_f32_16x16x32_bf16 v[40:43], v[166:169], v[198:201], v[40:43]
	v_mfma_f32_16x16x32_bf16 v[28:31], v[158:161], v[210:213], v[28:31]
	v_mfma_f32_16x16x32_bf16 v[24:27], v[166:169], v[210:213], v[24:27]
	v_mfma_f32_16x16x32_bf16 v[12:15], v[158:161], v[218:221], v[12:15]
	v_mfma_f32_16x16x32_bf16 v[8:11], v[166:169], v[218:221], v[8:11]
	s_setprio 0
	s_setprio 1
	v_mfma_f32_16x16x32_bf16 v[52:55], v[170:173], v[186:189], v[52:55]
	v_mfma_f32_16x16x32_bf16 v[48:51], v[178:181], v[186:189], v[48:51]
	v_mfma_f32_16x16x32_bf16 v[36:39], v[170:173], v[194:197], v[36:39]
	v_mfma_f32_16x16x32_bf16 v[32:35], v[178:181], v[194:197], v[32:35]
	v_mfma_f32_16x16x32_bf16 v[20:23], v[170:173], v[202:205], v[20:23]
	v_mfma_f32_16x16x32_bf16 v[16:19], v[178:181], v[202:205], v[16:19]
	v_mfma_f32_16x16x32_bf16 v[4:7], v[170:173], v[214:217], v[4:7]
	v_mfma_f32_16x16x32_bf16 v[0:3], v[178:181], v[214:217], v[0:3]
	v_mfma_f32_16x16x32_bf16 v[52:55], v[174:177], v[190:193], v[52:55]
	v_mfma_f32_16x16x32_bf16 v[48:51], v[182:185], v[190:193], v[48:51]
	v_mfma_f32_16x16x32_bf16 v[36:39], v[174:177], v[198:201], v[36:39]
	v_mfma_f32_16x16x32_bf16 v[32:35], v[182:185], v[198:201], v[32:35]
	v_mfma_f32_16x16x32_bf16 v[20:23], v[174:177], v[210:213], v[20:23]
	v_mfma_f32_16x16x32_bf16 v[16:19], v[182:185], v[210:213], v[16:19]
	v_mfma_f32_16x16x32_bf16 v[4:7], v[174:177], v[218:221], v[4:7]
	s_barrier
	v_mfma_f32_16x16x32_bf16 v[0:3], v[182:185], v[218:221], v[0:3]
	s_setprio 0
	s_add_i32 s50, s50, 2
	s_add_u32 s18, s18, 0x100
	s_addc_u32 s19, s19, 0
	s_cmp_gt_u32 s50, 41
	s_cbranch_scc0 .LBB0_1430
	s_add_u32 s18, s46, 0xffffff00
	s_addc_u32 s19, s47, -1
	s_and_b64 vcc, exec, s[6:7]
	s_cbranch_vccnz .LBB0_1433
	v_mov_b32_e32 v0, 0
	s_mov_b32 s39, s43
	s_mov_b32 s25, s44
	s_mov_b64 s[12:13], s[16:17]
	s_mov_b32 s40, s45
	v_mov_b32_e32 v1, v0
	v_mov_b64_e32 v[2:3], v[0:1]
	v_mov_b64_e32 v[4:5], v[0:1]
	v_mov_b64_e32 v[6:7], v[0:1]
	v_mov_b64_e32 v[8:9], v[0:1]
	v_mov_b64_e32 v[10:11], v[0:1]
	v_mov_b64_e32 v[12:13], v[0:1]
	v_mov_b64_e32 v[14:15], v[0:1]
	v_mov_b64_e32 v[16:17], v[0:1]
	v_mov_b64_e32 v[18:19], v[0:1]
	v_mov_b64_e32 v[20:21], v[0:1]
	v_mov_b64_e32 v[22:23], v[0:1]
	v_mov_b64_e32 v[24:25], v[0:1]
	v_mov_b64_e32 v[26:27], v[0:1]
	v_mov_b64_e32 v[28:29], v[0:1]
	v_mov_b64_e32 v[30:31], v[0:1]
	v_mov_b64_e32 v[32:33], v[0:1]
	v_mov_b64_e32 v[34:35], v[0:1]
	v_mov_b64_e32 v[36:37], v[0:1]
	v_mov_b64_e32 v[38:39], v[0:1]
	v_mov_b64_e32 v[40:41], v[0:1]
	v_mov_b64_e32 v[42:43], v[0:1]
	v_mov_b64_e32 v[44:45], v[0:1]
	v_mov_b64_e32 v[46:47], v[0:1]
	v_mov_b64_e32 v[48:49], v[0:1]
	v_mov_b64_e32 v[50:51], v[0:1]
	v_mov_b64_e32 v[52:53], v[0:1]
	v_mov_b64_e32 v[54:55], v[0:1]
	v_mov_b64_e32 v[56:57], v[0:1]
	v_mov_b64_e32 v[58:59], v[0:1]
	v_mov_b64_e32 v[60:61], v[0:1]
	v_mov_b64_e32 v[62:63], v[0:1]
	v_mov_b64_e32 v[64:65], v[0:1]
	v_mov_b64_e32 v[66:67], v[0:1]
	v_mov_b64_e32 v[68:69], v[0:1]
	v_mov_b64_e32 v[70:71], v[0:1]
	v_mov_b64_e32 v[72:73], v[0:1]
	v_mov_b64_e32 v[74:75], v[0:1]
	v_mov_b64_e32 v[76:77], v[0:1]
	v_mov_b64_e32 v[78:79], v[0:1]
	v_mov_b64_e32 v[80:81], v[0:1]
	v_mov_b64_e32 v[82:83], v[0:1]
	v_mov_b64_e32 v[84:85], v[0:1]
	v_mov_b64_e32 v[86:87], v[0:1]
	v_mov_b64_e32 v[88:89], v[0:1]
	v_mov_b64_e32 v[90:91], v[0:1]
	v_mov_b64_e32 v[92:93], v[0:1]
	v_mov_b64_e32 v[94:95], v[0:1]
	v_mov_b64_e32 v[96:97], v[0:1]
	v_mov_b64_e32 v[98:99], v[0:1]
	v_mov_b64_e32 v[100:101], v[0:1]
	v_mov_b64_e32 v[102:103], v[0:1]
	v_mov_b64_e32 v[104:105], v[0:1]
	v_mov_b64_e32 v[106:107], v[0:1]
	v_mov_b64_e32 v[108:109], v[0:1]
	v_mov_b64_e32 v[110:111], v[0:1]
	v_mov_b64_e32 v[112:113], v[0:1]
	v_mov_b64_e32 v[114:115], v[0:1]
	v_mov_b64_e32 v[116:117], v[0:1]
	v_mov_b64_e32 v[118:119], v[0:1]
	v_mov_b64_e32 v[120:121], v[0:1]
	v_mov_b64_e32 v[122:123], v[0:1]
	v_mov_b64_e32 v[124:125], v[0:1]
	v_mov_b64_e32 v[126:127], v[0:1]
	s_andn2_b64 vcc, exec, s[0:1]
	s_cbranch_vccnz .LBB0_1434
	s_branch .LBB0_1435
